# all K-loop MFMA blocks re-ordered into back-to-back accumulate chains (no other change)
# baseline (speedup 1.0000x reference)
; #define PG8_STAGE(bufoff, gbase, voff) do { const char* gb_ = (const char*)(gbase); asm volatile("" : "+s"(gb_)); _Pragma("unroll") for (int _i = 0; _i < 2; ++_i) { unsigned vo_ = (voff)[_i]; asm volatile("" : "+v"(vo_));        \
;         __builtin_amdgcn_global_load_lds((const unsigned*)(gb_ + vo_), (PG8_LAS unsigned*)(lds + (bufoff) + ldsw + _i * 8192), 16, 0, 0); } } while (0)
; #define PG8_LDA(dst, b, h) do { _Pragma("unroll") for (int m = 0; m < 4; ++m) _Pragma("unroll") for (int k = 0; k < 2; ++k) dst[m][k] = *(const PG8_LAS bf16x8*)(lds + PG8_SA(b, h) + aoff + m * 2048 + k * 1024); } while (0)
; #define PG8_LDB(dst, b, h) do { _Pragma("unroll") for (int n = 0; n < 2; ++n) _Pragma("unroll") for (int k = 0; k < 2; ++k) dst[n][k] = *(const PG8_LAS bf16x8*)(lds + PG8_SB(b, h) + boff + n * 2048 + k * 1024); } while (0)
; #define PG8_MMA(ai, bj, At, Bt) do { __builtin_amdgcn_s_setprio(1); _Pragma("unroll") for (int m = 0; m < 4; ++m) _Pragma("unroll") for (int n = 0; n < 2; ++n) _Pragma("unroll") for (int k = 0; k < 2; ++k) \
;         acc[ai][bj][m][n] = __builtin_amdgcn_mfma_f32_16x16x32_bf16(Bt[n][k], At[m][k], acc[ai][bj][m][n], 0, 0, 0); __builtin_amdgcn_s_setprio(0); } while (0)
; template <class Epi, class Sched, bool ALIGN_EPI = false, bool SP2 = false>
; __device__ __forceinline__ void gemm_phase(PG8_LAS unsigned char* lds, const Gemm g, const Sched& S, const Epi& E) {
;     ...
;         for (int t = 0; t < nt; t += 2) {
;             const bool last = (t == nt - 2);
;             const char* a1 = cA + (size_t)(t + 1) * kstep;
;             const char* a2 = last ? nA : cA + (size_t)(t + 2) * kstep; const char* b2 = last ? nB : cB + (size_t)(t + 2) * kstep;
;             const char* a3 = a2 + kstep; const char* b3 = b2 + kstep;
;             if (last && has_next) S.a_ready(nxt);
;             if constexpr (SP2) {
;             PG8_LDB(B0, 0, 0); PG8_LDB(B1, 0, 1); PG8_SCHED; PG8_LDA(At, 0, 0); PG8_STAGE(PG8_SA(1, 1), a1 + hstep, voffA);
;             PG8_WAIT_V(8); PG8_WAIT_L(0); PG8_BAR; PG8_MMA(0, 0, At, B0); PG8_MMA(0, 1, At, B1); PG8_BAR; PG8_SCHED;
;             PG8_LDA(At, 0, 1); PG8_STAGE(PG8_SB(0, 0), b2, voffB); PG8_STAGE(PG8_SB(0, 1), b2 + hstep, voffB); PG8_STAGE(PG8_SA(0, 0), a2, voffA);
;             PG8_WAIT_V(8); PG8_WAIT_L(0); PG8_BAR; PG8_MMA(1, 0, At, B0); PG8_MMA(1, 1, At, B1); PG8_BAR; PG8_SCHED;
.LBB0_232:
	s_add_u32 s2, s0, 0x100
	s_addc_u32 s3, s1, 0
	s_cmp_eq_u32 s30, 28
	s_cselect_b32 s10, s25, s2
	s_cselect_b32 s11, s24, s3
	s_cselect_b32 s8, s27, s28
	s_cselect_b32 s9, s26, s29
	s_add_u32 s6, s10, 0x80
	s_addc_u32 s7, s11, 0
	s_add_i32 s31, 0, 0x10000
	s_add_i32 s33, 0, 0x14000
	v_add_u32_e32 v78, s31, v221
	v_add_u32_e32 v158, s33, v221
	ds_read_b128 v[66:69], v78
	ds_read_b128 v[70:73], v78 offset:1024
	ds_read_b128 v[74:77], v78 offset:2048
	ds_read_b128 v[78:81], v78 offset:3072
	ds_read_b128 v[146:149], v158
	ds_read_b128 v[150:153], v158 offset:1024
	ds_read_b128 v[154:157], v158 offset:2048
	ds_read_b128 v[158:161], v158 offset:3072
	s_add_u32 s0, s0, 0x80080
	s_addc_u32 s1, s1, 0
	v_mov_b32_e32 v162, v1
	ds_read_b128 v[178:181], v223
	ds_read_b128 v[182:185], v223 offset:1024
	ds_read_b128 v[192:195], v223 offset:2048
	ds_read_b128 v[196:199], v223 offset:3072
	ds_read_b128 v[200:203], v223 offset:4096
	ds_read_b128 v[204:207], v223 offset:5120
	ds_read_b128 v[208:211], v223 offset:6144
	ds_read_b128 v[212:215], v223 offset:7168
	s_add_i32 m0, s13, 0xc000
	s_nop 0
	global_load_lds_dwordx4 v162, s[0:1]
	v_mov_b32_e32 v162, v191
	s_add_i32 m0, s13, 0xe000
	s_nop 0
	global_load_lds_dwordx4 v162, s[0:1]
	s_waitcnt vmcnt(8)
	s_waitcnt lgkmcnt(0)
	s_barrier
	s_setprio 1
	s_waitcnt lgkmcnt(0)
	v_mfma_f32_16x16x32_bf16 v[142:145], v[66:69], v[178:181], v[142:145]
	v_mfma_f32_16x16x32_bf16 v[142:145], v[70:73], v[182:185], v[142:145]
	v_mfma_f32_16x16x32_bf16 v[134:137], v[66:69], v[192:195], v[134:137]
	v_mfma_f32_16x16x32_bf16 v[134:137], v[70:73], v[196:199], v[134:137]
	v_mfma_f32_16x16x32_bf16 v[126:129], v[66:69], v[200:203], v[126:129]
	v_mfma_f32_16x16x32_bf16 v[126:129], v[70:73], v[204:207], v[126:129]
	v_mfma_f32_16x16x32_bf16 v[118:121], v[66:69], v[208:211], v[118:121]
	v_mfma_f32_16x16x32_bf16 v[118:121], v[70:73], v[212:215], v[118:121]
	v_mfma_f32_16x16x32_bf16 v[138:141], v[74:77], v[178:181], v[138:141]
	v_mfma_f32_16x16x32_bf16 v[138:141], v[78:81], v[182:185], v[138:141]
	v_mfma_f32_16x16x32_bf16 v[130:133], v[74:77], v[192:195], v[130:133]
	v_mfma_f32_16x16x32_bf16 v[130:133], v[78:81], v[196:199], v[130:133]
	v_mfma_f32_16x16x32_bf16 v[122:125], v[74:77], v[200:203], v[122:125]
	v_mfma_f32_16x16x32_bf16 v[122:125], v[78:81], v[204:207], v[122:125]
	v_mfma_f32_16x16x32_bf16 v[114:117], v[74:77], v[208:211], v[114:117]
	v_mfma_f32_16x16x32_bf16 v[114:117], v[78:81], v[212:215], v[114:117]
	s_setprio 0
	s_setprio 1
	v_mfma_f32_16x16x32_bf16 v[62:65], v[146:149], v[178:181], v[62:65]
	v_mfma_f32_16x16x32_bf16 v[62:65], v[150:153], v[182:185], v[62:65]
	v_mfma_f32_16x16x32_bf16 v[54:57], v[146:149], v[192:195], v[54:57]
	v_mfma_f32_16x16x32_bf16 v[54:57], v[150:153], v[196:199], v[54:57]
	v_mfma_f32_16x16x32_bf16 v[46:49], v[146:149], v[200:203], v[46:49]
	v_mfma_f32_16x16x32_bf16 v[46:49], v[150:153], v[204:207], v[46:49]
	v_mfma_f32_16x16x32_bf16 v[38:41], v[146:149], v[208:211], v[38:41]
	v_mfma_f32_16x16x32_bf16 v[38:41], v[150:153], v[212:215], v[38:41]
	v_mfma_f32_16x16x32_bf16 v[58:61], v[154:157], v[178:181], v[58:61]
	v_mfma_f32_16x16x32_bf16 v[58:61], v[158:161], v[182:185], v[58:61]
	v_mfma_f32_16x16x32_bf16 v[50:53], v[154:157], v[192:195], v[50:53]
	v_mfma_f32_16x16x32_bf16 v[50:53], v[158:161], v[196:199], v[50:53]
	v_mfma_f32_16x16x32_bf16 v[42:45], v[154:157], v[200:203], v[42:45]
	v_mfma_f32_16x16x32_bf16 v[42:45], v[158:161], v[204:207], v[42:45]
	v_mfma_f32_16x16x32_bf16 v[34:37], v[154:157], v[208:211], v[34:37]
	v_mfma_f32_16x16x32_bf16 v[34:37], v[158:161], v[212:215], v[34:37]
	s_setprio 0
	s_barrier
	s_mov_b64 s[0:1], s[8:9]
	v_mov_b32_e32 v162, v189
	s_add_i32 s31, s31, s12
	ds_read_b128 v[178:181], v223 offset:16384
	ds_read_b128 v[182:185], v223 offset:17408
	ds_read_b128 v[192:195], v223 offset:18432
	ds_read_b128 v[196:199], v223 offset:19456
	ds_read_b128 v[200:203], v223 offset:20480
	ds_read_b128 v[204:207], v223 offset:21504
	ds_read_b128 v[208:211], v223 offset:22528
	ds_read_b128 v[212:215], v223 offset:23552
	s_mov_b32 m0, s31
	s_nop 0
	global_load_lds_dwordx4 v162, s[0:1]
	v_mov_b32_e32 v162, v219
	s_add_i32 m0, s31, 0x2000
	s_nop 0
	global_load_lds_dwordx4 v162, s[0:1]
	s_add_u32 s0, s8, 0x80000
	s_addc_u32 s1, s9, 0
	v_mov_b32_e32 v162, v189
	s_add_i32 s31, s33, s12
	s_mov_b32 m0, s31
	s_nop 0
	global_load_lds_dwordx4 v162, s[0:1]
	v_mov_b32_e32 v162, v219
	s_add_i32 m0, s31, 0x2000
	s_nop 0
	global_load_lds_dwordx4 v162, s[0:1]
	s_mov_b64 s[0:1], s[10:11]
	v_mov_b32_e32 v162, v1
	s_mov_b32 m0, s13
	s_nop 0
	global_load_lds_dwordx4 v162, s[0:1]
	v_mov_b32_e32 v162, v191
	s_mov_b32 m0, s14
	s_nop 0
	global_load_lds_dwordx4 v162, s[0:1]
	s_waitcnt vmcnt(8)
	s_waitcnt lgkmcnt(0)
	s_barrier
; #define PG8_STAGE(bufoff, gbase, voff) do { const char* gb_ = (const char*)(gbase); asm volatile("" : "+s"(gb_)); _Pragma("unroll") for (int _i = 0; _i < 2; ++_i) { unsigned vo_ = (voff)[_i]; asm volatile("" : "+v"(vo_));        \
;         __builtin_amdgcn_global_load_lds((const unsigned*)(gb_ + vo_), (PG8_LAS unsigned*)(lds + (bufoff) + ldsw + _i * 8192), 16, 0, 0); } } while (0)
; #define PG8_LDA(dst, b, h) do { _Pragma("unroll") for (int m = 0; m < 4; ++m) _Pragma("unroll") for (int k = 0; k < 2; ++k) dst[m][k] = *(const PG8_LAS bf16x8*)(lds + PG8_SA(b, h) + aoff + m * 2048 + k * 1024); } while (0)
; #define PG8_LDB(dst, b, h) do { _Pragma("unroll") for (int n = 0; n < 2; ++n) _Pragma("unroll") for (int k = 0; k < 2; ++k) dst[n][k] = *(const PG8_LAS bf16x8*)(lds + PG8_SB(b, h) + boff + n * 2048 + k * 1024); } while (0)
; #define PG8_MMA(ai, bj, At, Bt) do { __builtin_amdgcn_s_setprio(1); _Pragma("unroll") for (int m = 0; m < 4; ++m) _Pragma("unroll") for (int n = 0; n < 2; ++n) _Pragma("unroll") for (int k = 0; k < 2; ++k) \
;         acc[ai][bj][m][n] = __builtin_amdgcn_mfma_f32_16x16x32_bf16(Bt[n][k], At[m][k], acc[ai][bj][m][n], 0, 0, 0); __builtin_amdgcn_s_setprio(0); } while (0)
; #define PG8_WAIT_V(n) asm volatile("s_waitcnt vmcnt(" #n ")" ::: "memory")
; #define PG8_WAIT_L(n) asm volatile("s_waitcnt lgkmcnt(" #n ")" ::: "memory")
; #define PG8_BAR __builtin_amdgcn_s_barrier()
; #define PG8_SCHED __builtin_amdgcn_sched_barrier(0)
; template <class Epi, class Sched, bool ALIGN_EPI = false, bool SP2 = false>
; __device__ __forceinline__ void gemm_phase(PG8_LAS unsigned char* lds, const Gemm g, const Sched& S, const Epi& E) {
;     ...
;             PG8_WAIT_V(8); PG8_WAIT_L(0); PG8_BAR; PG8_MMA(1, 0, At, B0); PG8_MMA(1, 1, At, B1); PG8_BAR; PG8_SCHED;
;             PG8_LDB(B0, 1, 0); PG8_LDB(B1, 1, 1); PG8_SCHED; PG8_LDA(At, 1, 0); PG8_STAGE(PG8_SA(0, 1), a2 + hstep, voffA);
;             PG8_WAIT_V(8); PG8_WAIT_L(0); PG8_BAR; PG8_MMA(0, 0, At, B0); PG8_MMA(0, 1, At, B1); PG8_BAR; PG8_SCHED;
;             PG8_LDA(At, 1, 1); PG8_STAGE(PG8_SB(1, 0), b3, voffB); PG8_STAGE(PG8_SB(1, 1), b3 + hstep, voffB); PG8_STAGE(PG8_SA(1, 0), a3, voffA);
	s_setprio 1
	s_waitcnt lgkmcnt(0)
	v_mfma_f32_16x16x32_bf16 v[110:113], v[66:69], v[178:181], v[110:113]
	v_mfma_f32_16x16x32_bf16 v[110:113], v[70:73], v[182:185], v[110:113]
	v_mfma_f32_16x16x32_bf16 v[102:105], v[66:69], v[192:195], v[102:105]
	v_mfma_f32_16x16x32_bf16 v[102:105], v[70:73], v[196:199], v[102:105]
	v_mfma_f32_16x16x32_bf16 v[94:97], v[66:69], v[200:203], v[94:97]
	v_mfma_f32_16x16x32_bf16 v[94:97], v[70:73], v[204:207], v[94:97]
	v_mfma_f32_16x16x32_bf16 v[66:69], v[66:69], v[208:211], v[86:89]
	v_mfma_f32_16x16x32_bf16 v[66:69], v[70:73], v[212:215], v[66:69]
	v_mfma_f32_16x16x32_bf16 v[106:109], v[74:77], v[178:181], v[106:109]
	v_mfma_f32_16x16x32_bf16 v[106:109], v[78:81], v[182:185], v[106:109]
	v_mfma_f32_16x16x32_bf16 v[98:101], v[74:77], v[192:195], v[98:101]
	v_mfma_f32_16x16x32_bf16 v[98:101], v[78:81], v[196:199], v[98:101]
	v_mfma_f32_16x16x32_bf16 v[90:93], v[74:77], v[200:203], v[90:93]
	v_mfma_f32_16x16x32_bf16 v[90:93], v[78:81], v[204:207], v[90:93]
	v_mfma_f32_16x16x32_bf16 v[70:73], v[74:77], v[208:211], v[82:85]
	v_mfma_f32_16x16x32_bf16 v[70:73], v[78:81], v[212:215], v[70:73]
	s_setprio 0
	s_setprio 1
	v_mfma_f32_16x16x32_bf16 v[30:33], v[146:149], v[178:181], v[30:33]
	v_mfma_f32_16x16x32_bf16 v[30:33], v[150:153], v[182:185], v[30:33]
	v_mfma_f32_16x16x32_bf16 v[22:25], v[146:149], v[192:195], v[22:25]
	v_mfma_f32_16x16x32_bf16 v[22:25], v[150:153], v[196:199], v[22:25]
	v_mfma_f32_16x16x32_bf16 v[14:17], v[146:149], v[200:203], v[14:17]
	v_mfma_f32_16x16x32_bf16 v[14:17], v[150:153], v[204:207], v[14:17]
	v_mfma_f32_16x16x32_bf16 v[6:9], v[146:149], v[208:211], v[6:9]
	v_mfma_f32_16x16x32_bf16 v[6:9], v[150:153], v[212:215], v[6:9]
	v_mfma_f32_16x16x32_bf16 v[26:29], v[154:157], v[178:181], v[26:29]
	v_mfma_f32_16x16x32_bf16 v[26:29], v[158:161], v[182:185], v[26:29]
	v_mfma_f32_16x16x32_bf16 v[18:21], v[154:157], v[192:195], v[18:21]
	v_mfma_f32_16x16x32_bf16 v[18:21], v[158:161], v[196:199], v[18:21]
	v_mfma_f32_16x16x32_bf16 v[10:13], v[154:157], v[200:203], v[10:13]
	v_mfma_f32_16x16x32_bf16 v[10:13], v[158:161], v[204:207], v[10:13]
	v_mfma_f32_16x16x32_bf16 v[2:5], v[154:157], v[208:211], v[2:5]
	v_mfma_f32_16x16x32_bf16 v[2:5], v[158:161], v[212:215], v[2:5]
	s_setprio 0
	s_barrier
	s_add_i32 s31, 0, 0x18000
	v_add_u32_e32 v86, s31, v221
	s_add_i32 s33, 0, 0x1c000
	ds_read_b128 v[74:77], v86
	ds_read_b128 v[78:81], v86 offset:1024
	ds_read_b128 v[82:85], v86 offset:2048
	ds_read_b128 v[146:149], v86 offset:3072
	v_add_u32_e32 v86, s33, v221
	ds_read_b128 v[150:153], v86
	ds_read_b128 v[154:157], v86 offset:1024
	ds_read_b128 v[158:161], v86 offset:2048
	ds_read_b128 v[178:181], v86 offset:3072
	s_add_u32 s0, s10, 0x80000
	s_addc_u32 s1, s11, 0
	v_mov_b32_e32 v162, v1
	s_mov_b32 m0, s15
	ds_read_b128 v[86:89], v223 offset:32768
	ds_read_b128 v[182:185], v223 offset:33792
	ds_read_b128 v[192:195], v223 offset:34816
	ds_read_b128 v[196:199], v223 offset:35840
	ds_read_b128 v[200:203], v223 offset:36864
	ds_read_b128 v[204:207], v223 offset:37888
	ds_read_b128 v[208:211], v223 offset:38912
	ds_read_b128 v[212:215], v223 offset:39936
	s_nop 0
	global_load_lds_dwordx4 v162, s[0:1]
	v_mov_b32_e32 v162, v191
	s_mov_b32 m0, s16
	s_nop 0
	global_load_lds_dwordx4 v162, s[0:1]
	s_waitcnt vmcnt(8)
	s_waitcnt lgkmcnt(0)
	s_barrier
	s_setprio 1
	s_waitcnt lgkmcnt(0)
	v_mfma_f32_16x16x32_bf16 v[142:145], v[74:77], v[86:89], v[142:145]
	v_mfma_f32_16x16x32_bf16 v[142:145], v[78:81], v[182:185], v[142:145]
	v_mfma_f32_16x16x32_bf16 v[134:137], v[74:77], v[192:195], v[134:137]
	v_mfma_f32_16x16x32_bf16 v[134:137], v[78:81], v[196:199], v[134:137]
	v_mfma_f32_16x16x32_bf16 v[126:129], v[74:77], v[200:203], v[126:129]
	v_mfma_f32_16x16x32_bf16 v[126:129], v[78:81], v[204:207], v[126:129]
	v_mfma_f32_16x16x32_bf16 v[118:121], v[74:77], v[208:211], v[118:121]
	v_mfma_f32_16x16x32_bf16 v[118:121], v[78:81], v[212:215], v[118:121]
	v_mfma_f32_16x16x32_bf16 v[138:141], v[82:85], v[86:89], v[138:141]
	v_mfma_f32_16x16x32_bf16 v[138:141], v[146:149], v[182:185], v[138:141]
	v_mfma_f32_16x16x32_bf16 v[130:133], v[82:85], v[192:195], v[130:133]
	v_mfma_f32_16x16x32_bf16 v[130:133], v[146:149], v[196:199], v[130:133]
	v_mfma_f32_16x16x32_bf16 v[122:125], v[82:85], v[200:203], v[122:125]
	v_mfma_f32_16x16x32_bf16 v[122:125], v[146:149], v[204:207], v[122:125]
	v_mfma_f32_16x16x32_bf16 v[114:117], v[82:85], v[208:211], v[114:117]
	v_mfma_f32_16x16x32_bf16 v[114:117], v[146:149], v[212:215], v[114:117]
	s_setprio 0
	s_setprio 1
	v_mfma_f32_16x16x32_bf16 v[62:65], v[150:153], v[86:89], v[62:65]
	v_mfma_f32_16x16x32_bf16 v[62:65], v[154:157], v[182:185], v[62:65]
	v_mfma_f32_16x16x32_bf16 v[54:57], v[150:153], v[192:195], v[54:57]
	v_mfma_f32_16x16x32_bf16 v[54:57], v[154:157], v[196:199], v[54:57]
	v_mfma_f32_16x16x32_bf16 v[46:49], v[150:153], v[200:203], v[46:49]
	v_mfma_f32_16x16x32_bf16 v[46:49], v[154:157], v[204:207], v[46:49]
	v_mfma_f32_16x16x32_bf16 v[38:41], v[150:153], v[208:211], v[38:41]
	v_mfma_f32_16x16x32_bf16 v[38:41], v[154:157], v[212:215], v[38:41]
	v_mfma_f32_16x16x32_bf16 v[58:61], v[158:161], v[86:89], v[58:61]
	v_mfma_f32_16x16x32_bf16 v[58:61], v[178:181], v[182:185], v[58:61]
	v_mfma_f32_16x16x32_bf16 v[50:53], v[158:161], v[192:195], v[50:53]
	v_mfma_f32_16x16x32_bf16 v[50:53], v[178:181], v[196:199], v[50:53]
	v_mfma_f32_16x16x32_bf16 v[42:45], v[158:161], v[200:203], v[42:45]
	v_mfma_f32_16x16x32_bf16 v[42:45], v[178:181], v[204:207], v[42:45]
	v_mfma_f32_16x16x32_bf16 v[34:37], v[158:161], v[208:211], v[34:37]
	v_mfma_f32_16x16x32_bf16 v[34:37], v[178:181], v[212:215], v[34:37]
	s_setprio 0
	s_barrier
; #define PG8_STAGE(bufoff, gbase, voff) do { const char* gb_ = (const char*)(gbase); asm volatile("" : "+s"(gb_)); _Pragma("unroll") for (int _i = 0; _i < 2; ++_i) { unsigned vo_ = (voff)[_i]; asm volatile("" : "+v"(vo_));        \
;         __builtin_amdgcn_global_load_lds((const unsigned*)(gb_ + vo_), (PG8_LAS unsigned*)(lds + (bufoff) + ldsw + _i * 8192), 16, 0, 0); } } while (0)
; #define PG8_LDA(dst, b, h) do { _Pragma("unroll") for (int m = 0; m < 4; ++m) _Pragma("unroll") for (int k = 0; k < 2; ++k) dst[m][k] = *(const PG8_LAS bf16x8*)(lds + PG8_SA(b, h) + aoff + m * 2048 + k * 1024); } while (0)
; #define PG8_MMA(ai, bj, At, Bt) do { __builtin_amdgcn_s_setprio(1); _Pragma("unroll") for (int m = 0; m < 4; ++m) _Pragma("unroll") for (int n = 0; n < 2; ++n) _Pragma("unroll") for (int k = 0; k < 2; ++k) \
;         acc[ai][bj][m][n] = __builtin_amdgcn_mfma_f32_16x16x32_bf16(Bt[n][k], At[m][k], acc[ai][bj][m][n], 0, 0, 0); __builtin_amdgcn_s_setprio(0); } while (0)
; #define PG8_WAIT_V(n) asm volatile("s_waitcnt vmcnt(" #n ")" ::: "memory")
; #define PG8_WAIT_L(n) asm volatile("s_waitcnt lgkmcnt(" #n ")" ::: "memory")
; #define PG8_BAR __builtin_amdgcn_s_barrier()
; #define PG8_SCHED __builtin_amdgcn_sched_barrier(0)
; template <class Epi, class Sched, bool ALIGN_EPI = false, bool SP2 = false>
; __device__ __forceinline__ void gemm_phase(PG8_LAS unsigned char* lds, const Gemm g, const Sched& S, const Epi& E) {
;     ...
;             PG8_LDA(At, 1, 1); PG8_STAGE(PG8_SB(1, 0), b3, voffB); PG8_STAGE(PG8_SB(1, 1), b3 + hstep, voffB); PG8_STAGE(PG8_SA(1, 0), a3, voffA);
;             PG8_WAIT_V(8); PG8_WAIT_L(0); PG8_BAR; PG8_MMA(1, 0, At, B0); PG8_MMA(1, 1, At, B1); PG8_BAR; PG8_SCHED;
;     ...
;         if constexpr (ALIGN_EPI) { if (wr == 0) PG8_BAR; }
	s_add_u32 s0, s8, 0x80
	s_addc_u32 s1, s9, 0
	v_mov_b32_e32 v86, v189
	s_add_i32 s10, s31, s12
	ds_read_b128 v[182:185], v223 offset:49152
	ds_read_b128 v[192:195], v223 offset:50176
	ds_read_b128 v[196:199], v223 offset:51200
	ds_read_b128 v[200:203], v223 offset:52224
	ds_read_b128 v[204:207], v223 offset:53248
	ds_read_b128 v[208:211], v223 offset:54272
	ds_read_b128 v[212:215], v223 offset:55296
	ds_read_b128 v[224:227], v223 offset:56320
	s_mov_b32 m0, s10
	s_nop 0
	global_load_lds_dwordx4 v86, s[0:1]
	v_mov_b32_e32 v86, v219
	s_add_i32 m0, s10, 0x2000
	s_nop 0
	global_load_lds_dwordx4 v86, s[0:1]
	s_add_u32 s0, s8, 0x80080
	s_addc_u32 s1, s9, 0
	v_mov_b32_e32 v86, v189
	s_add_i32 s8, s33, s12
	s_mov_b32 m0, s8
	s_nop 0
	global_load_lds_dwordx4 v86, s[0:1]
	v_mov_b32_e32 v86, v219
	s_add_i32 m0, s8, 0x2000
	s_nop 0
	global_load_lds_dwordx4 v86, s[0:1]
	v_mov_b32_e32 v86, v1
	s_mov_b32 m0, s19
	s_nop 0
	global_load_lds_dwordx4 v86, s[6:7]
	v_mov_b32_e32 v86, v191
	s_mov_b32 m0, s20
	s_nop 0
	global_load_lds_dwordx4 v86, s[6:7]
	s_waitcnt vmcnt(8)
	s_waitcnt lgkmcnt(0)
	s_barrier
	s_setprio 1
	s_waitcnt lgkmcnt(0)
	v_mfma_f32_16x16x32_bf16 v[86:89], v[74:77], v[182:185], v[110:113]
	v_mfma_f32_16x16x32_bf16 v[110:113], v[78:81], v[192:195], v[86:89]
	v_mfma_f32_16x16x32_bf16 v[66:69], v[74:77], v[212:215], v[66:69]
	v_mfma_f32_16x16x32_bf16 v[86:89], v[82:85], v[182:185], v[106:109]
	v_mfma_f32_16x16x32_bf16 v[106:109], v[146:149], v[192:195], v[86:89]
	v_mfma_f32_16x16x32_bf16 v[86:89], v[74:77], v[196:199], v[102:105]
	v_mfma_f32_16x16x32_bf16 v[102:105], v[78:81], v[200:203], v[86:89]
	v_mfma_f32_16x16x32_bf16 v[86:89], v[82:85], v[196:199], v[98:101]
	v_mfma_f32_16x16x32_bf16 v[98:101], v[146:149], v[200:203], v[86:89]
	v_mfma_f32_16x16x32_bf16 v[86:89], v[74:77], v[204:207], v[94:97]
	v_mfma_f32_16x16x32_bf16 v[94:97], v[78:81], v[208:211], v[86:89]
	v_mfma_f32_16x16x32_bf16 v[86:89], v[82:85], v[204:207], v[90:93]
	v_mfma_f32_16x16x32_bf16 v[90:93], v[146:149], v[208:211], v[86:89]
	v_mfma_f32_16x16x32_bf16 v[86:89], v[78:81], v[224:227], v[66:69]
	v_mfma_f32_16x16x32_bf16 v[66:69], v[82:85], v[212:215], v[70:73]
	v_mfma_f32_16x16x32_bf16 v[82:85], v[146:149], v[224:227], v[66:69]
	s_setprio 0
	s_setprio 1
	v_mfma_f32_16x16x32_bf16 v[30:33], v[150:153], v[182:185], v[30:33]
	v_mfma_f32_16x16x32_bf16 v[30:33], v[154:157], v[192:195], v[30:33]
	v_mfma_f32_16x16x32_bf16 v[22:25], v[150:153], v[196:199], v[22:25]
	v_mfma_f32_16x16x32_bf16 v[22:25], v[154:157], v[200:203], v[22:25]
	v_mfma_f32_16x16x32_bf16 v[14:17], v[150:153], v[204:207], v[14:17]
	v_mfma_f32_16x16x32_bf16 v[14:17], v[154:157], v[208:211], v[14:17]
	v_mfma_f32_16x16x32_bf16 v[6:9], v[150:153], v[212:215], v[6:9]
	v_mfma_f32_16x16x32_bf16 v[6:9], v[154:157], v[224:227], v[6:9]
	v_mfma_f32_16x16x32_bf16 v[26:29], v[158:161], v[182:185], v[26:29]
	v_mfma_f32_16x16x32_bf16 v[26:29], v[178:181], v[192:195], v[26:29]
	v_mfma_f32_16x16x32_bf16 v[18:21], v[158:161], v[196:199], v[18:21]
	v_mfma_f32_16x16x32_bf16 v[18:21], v[178:181], v[200:203], v[18:21]
	v_mfma_f32_16x16x32_bf16 v[10:13], v[158:161], v[204:207], v[10:13]
	v_mfma_f32_16x16x32_bf16 v[10:13], v[178:181], v[208:211], v[10:13]
	v_mfma_f32_16x16x32_bf16 v[2:5], v[158:161], v[212:215], v[2:5]
	v_mfma_f32_16x16x32_bf16 v[2:5], v[178:181], v[224:227], v[2:5]
	s_setprio 0
	s_barrier
	s_add_i32 s30, s30, 2
	s_add_u32 s28, s28, 0x100
	s_addc_u32 s29, s29, 0
	s_cmp_gt_u32 s30, 29
	s_mov_b64 s[0:1], s[2:3]
	s_cbranch_scc0 .LBB0_232
	s_and_b64 vcc, exec, s[44:45]
	s_cbranch_vccz .LBB0_235
	s_barrier

; #define PG8_STAGE(bufoff, gbase, voff) do { const char* gb_ = (const char*)(gbase); asm volatile("" : "+s"(gb_)); _Pragma("unroll") for (int _i = 0; _i < 2; ++_i) { unsigned vo_ = (voff)[_i]; asm volatile("" : "+v"(vo_));        \
;         __builtin_amdgcn_global_load_lds((const unsigned*)(gb_ + vo_), (PG8_LAS unsigned*)(lds + (bufoff) + ldsw + _i * 8192), 16, 0, 0); } } while (0)
; #define PG8_LDA(dst, b, h) do { _Pragma("unroll") for (int m = 0; m < 4; ++m) _Pragma("unroll") for (int k = 0; k < 2; ++k) dst[m][k] = *(const PG8_LAS bf16x8*)(lds + PG8_SA(b, h) + aoff + m * 2048 + k * 1024); } while (0)
; #define PG8_LDB(dst, b, h) do { _Pragma("unroll") for (int n = 0; n < 2; ++n) _Pragma("unroll") for (int k = 0; k < 2; ++k) dst[n][k] = *(const PG8_LAS bf16x8*)(lds + PG8_SB(b, h) + boff + n * 2048 + k * 1024); } while (0)
; #define PG8_MMA(ai, bj, At, Bt) do { __builtin_amdgcn_s_setprio(1); _Pragma("unroll") for (int m = 0; m < 4; ++m) _Pragma("unroll") for (int n = 0; n < 2; ++n) _Pragma("unroll") for (int k = 0; k < 2; ++k) \
;         acc[ai][bj][m][n] = __builtin_amdgcn_mfma_f32_16x16x32_bf16(Bt[n][k], At[m][k], acc[ai][bj][m][n], 0, 0, 0); __builtin_amdgcn_s_setprio(0); } while (0)
; template <class Epi, class Sched, bool ALIGN_EPI = false, bool SP2 = false>
; __device__ __forceinline__ void gemm_phase(PG8_LAS unsigned char* lds, const Gemm g, const Sched& S, const Epi& E) {
;     ...
;         for (int t = 0; t < nt; t += 2) {
;             const bool last = (t == nt - 2);
;             const char* a1 = cA + (size_t)(t + 1) * kstep;
;             const char* a2 = last ? nA : cA + (size_t)(t + 2) * kstep; const char* b2 = last ? nB : cB + (size_t)(t + 2) * kstep;
;             const char* a3 = a2 + kstep; const char* b3 = b2 + kstep;
;             if (last && has_next) S.a_ready(nxt);
;             if constexpr (SP2) {
;             PG8_LDB(B0, 0, 0); PG8_LDB(B1, 0, 1); PG8_SCHED; PG8_LDA(At, 0, 0); PG8_STAGE(PG8_SA(1, 1), a1 + hstep, voffA);
;             PG8_WAIT_V(8); PG8_WAIT_L(0); PG8_BAR; PG8_MMA(0, 0, At, B0); PG8_MMA(0, 1, At, B1); PG8_BAR; PG8_SCHED;
;             PG8_LDA(At, 0, 1); PG8_STAGE(PG8_SB(0, 0), b2, voffB); PG8_STAGE(PG8_SB(0, 1), b2 + hstep, voffB); PG8_STAGE(PG8_SA(0, 0), a2, voffA);
;             PG8_WAIT_V(8); PG8_WAIT_L(0); PG8_BAR; PG8_MMA(1, 0, At, B0); PG8_MMA(1, 1, At, B1); PG8_BAR; PG8_SCHED;
.LBB0_555:
	s_add_u32 s6, s4, 0x100
	s_addc_u32 s7, s5, 0
	s_cmp_eq_u32 s51, 28
	s_cselect_b32 s12, s35, s6
	s_cselect_b32 s13, s34, s7
	s_cselect_b32 s10, s39, s40
	s_cselect_b32 s11, s38, s49
	s_add_u32 s8, s12, 0x80
	s_addc_u32 s9, s13, 0
	s_add_i32 s56, 0, 0x10000
	s_add_i32 s57, 0, 0x14000
	v_add_u32_e32 v102, s56, v208
	v_add_u32_e32 v158, s57, v208
	ds_read_b128 v[26:29], v102
	ds_read_b128 v[30:33], v102 offset:1024
	ds_read_b128 v[98:101], v102 offset:2048
	ds_read_b128 v[102:105], v102 offset:3072
	ds_read_b128 v[146:149], v158
	ds_read_b128 v[150:153], v158 offset:1024
	ds_read_b128 v[154:157], v158 offset:2048
	ds_read_b128 v[158:161], v158 offset:3072
	s_add_u32 s4, s4, 0x80080
	s_addc_u32 s5, s5, 0
	v_mov_b32_e32 v211, v1
	ds_read_b128 v[178:181], v210
	ds_read_b128 v[182:185], v210 offset:1024
	ds_read_b128 v[186:189], v210 offset:2048
	ds_read_b128 v[190:193], v210 offset:3072
	ds_read_b128 v[194:197], v210 offset:4096
	ds_read_b128 v[198:201], v210 offset:5120
	ds_read_b128 v[202:205], v210 offset:6144
	ds_read_b128 v[212:215], v210 offset:7168
	s_add_i32 m0, s18, 0xc000
	s_nop 0
	global_load_lds_dwordx4 v211, s[4:5]
	v_mov_b32_e32 v211, v164
	s_add_i32 m0, s18, 0xe000
	s_nop 0
	global_load_lds_dwordx4 v211, s[4:5]
	s_waitcnt vmcnt(8)
	s_waitcnt lgkmcnt(0)
	s_barrier
	s_setprio 1
	s_waitcnt lgkmcnt(0)
	v_mfma_f32_16x16x32_bf16 v[142:145], v[26:29], v[178:181], v[142:145]
	v_mfma_f32_16x16x32_bf16 v[142:145], v[30:33], v[182:185], v[142:145]
	v_mfma_f32_16x16x32_bf16 v[134:137], v[26:29], v[186:189], v[134:137]
	v_mfma_f32_16x16x32_bf16 v[134:137], v[30:33], v[190:193], v[134:137]
	v_mfma_f32_16x16x32_bf16 v[126:129], v[26:29], v[194:197], v[126:129]
	v_mfma_f32_16x16x32_bf16 v[126:129], v[30:33], v[198:201], v[126:129]
	v_mfma_f32_16x16x32_bf16 v[118:121], v[26:29], v[202:205], v[118:121]
	v_mfma_f32_16x16x32_bf16 v[118:121], v[30:33], v[212:215], v[118:121]
	v_mfma_f32_16x16x32_bf16 v[138:141], v[98:101], v[178:181], v[138:141]
	v_mfma_f32_16x16x32_bf16 v[138:141], v[102:105], v[182:185], v[138:141]
	v_mfma_f32_16x16x32_bf16 v[130:133], v[98:101], v[186:189], v[130:133]
	v_mfma_f32_16x16x32_bf16 v[130:133], v[102:105], v[190:193], v[130:133]
	v_mfma_f32_16x16x32_bf16 v[122:125], v[98:101], v[194:197], v[122:125]
	v_mfma_f32_16x16x32_bf16 v[122:125], v[102:105], v[198:201], v[122:125]
	v_mfma_f32_16x16x32_bf16 v[114:117], v[98:101], v[202:205], v[114:117]
	v_mfma_f32_16x16x32_bf16 v[114:117], v[102:105], v[212:215], v[114:117]
	s_setprio 0
	s_setprio 1
	v_mfma_f32_16x16x32_bf16 v[70:73], v[146:149], v[178:181], v[70:73]
	v_mfma_f32_16x16x32_bf16 v[70:73], v[150:153], v[182:185], v[70:73]
	v_mfma_f32_16x16x32_bf16 v[62:65], v[146:149], v[186:189], v[62:65]
	v_mfma_f32_16x16x32_bf16 v[62:65], v[150:153], v[190:193], v[62:65]
	v_mfma_f32_16x16x32_bf16 v[54:57], v[146:149], v[194:197], v[54:57]
	v_mfma_f32_16x16x32_bf16 v[54:57], v[150:153], v[198:201], v[54:57]
	v_mfma_f32_16x16x32_bf16 v[46:49], v[146:149], v[202:205], v[46:49]
	v_mfma_f32_16x16x32_bf16 v[46:49], v[150:153], v[212:215], v[46:49]
	v_mfma_f32_16x16x32_bf16 v[66:69], v[154:157], v[178:181], v[66:69]
	v_mfma_f32_16x16x32_bf16 v[66:69], v[158:161], v[182:185], v[66:69]
	v_mfma_f32_16x16x32_bf16 v[58:61], v[154:157], v[186:189], v[58:61]
	v_mfma_f32_16x16x32_bf16 v[58:61], v[158:161], v[190:193], v[58:61]
	v_mfma_f32_16x16x32_bf16 v[50:53], v[154:157], v[194:197], v[50:53]
	v_mfma_f32_16x16x32_bf16 v[50:53], v[158:161], v[198:201], v[50:53]
	v_mfma_f32_16x16x32_bf16 v[42:45], v[154:157], v[202:205], v[42:45]
	v_mfma_f32_16x16x32_bf16 v[42:45], v[158:161], v[212:215], v[42:45]
	s_setprio 0
	s_barrier
	s_mov_b64 s[4:5], s[10:11]
	v_mov_b32_e32 v211, v162
	s_add_i32 s56, s56, s17
	ds_read_b128 v[178:181], v210 offset:16384
	ds_read_b128 v[182:185], v210 offset:17408
	ds_read_b128 v[186:189], v210 offset:18432
	ds_read_b128 v[190:193], v210 offset:19456
	ds_read_b128 v[194:197], v210 offset:20480
	ds_read_b128 v[198:201], v210 offset:21504
	ds_read_b128 v[202:205], v210 offset:22528
	ds_read_b128 v[212:215], v210 offset:23552
	s_mov_b32 m0, s56
	s_nop 0
	global_load_lds_dwordx4 v211, s[4:5]
	v_mov_b32_e32 v211, v206
	s_add_i32 m0, s56, 0x2000
	s_nop 0
	global_load_lds_dwordx4 v211, s[4:5]
	s_add_u32 s4, s10, 0x80000
	s_addc_u32 s5, s11, 0
	v_mov_b32_e32 v211, v162
	s_add_i32 s56, s57, s17
	s_mov_b32 m0, s56
	s_nop 0
	global_load_lds_dwordx4 v211, s[4:5]
	v_mov_b32_e32 v211, v206
	s_add_i32 m0, s56, 0x2000
	s_nop 0
	global_load_lds_dwordx4 v211, s[4:5]
	s_mov_b64 s[4:5], s[12:13]
	v_mov_b32_e32 v211, v1
	s_mov_b32 m0, s18
	s_nop 0
	global_load_lds_dwordx4 v211, s[4:5]
	v_mov_b32_e32 v211, v164
	s_mov_b32 m0, s19
	s_nop 0
	global_load_lds_dwordx4 v211, s[4:5]
	s_waitcnt vmcnt(8)
	s_waitcnt lgkmcnt(0)
	s_barrier
; #define PG8_STAGE(bufoff, gbase, voff) do { const char* gb_ = (const char*)(gbase); asm volatile("" : "+s"(gb_)); _Pragma("unroll") for (int _i = 0; _i < 2; ++_i) { unsigned vo_ = (voff)[_i]; asm volatile("" : "+v"(vo_));        \
;         __builtin_amdgcn_global_load_lds((const unsigned*)(gb_ + vo_), (PG8_LAS unsigned*)(lds + (bufoff) + ldsw + _i * 8192), 16, 0, 0); } } while (0)
; #define PG8_LDA(dst, b, h) do { _Pragma("unroll") for (int m = 0; m < 4; ++m) _Pragma("unroll") for (int k = 0; k < 2; ++k) dst[m][k] = *(const PG8_LAS bf16x8*)(lds + PG8_SA(b, h) + aoff + m * 2048 + k * 1024); } while (0)
; #define PG8_LDB(dst, b, h) do { _Pragma("unroll") for (int n = 0; n < 2; ++n) _Pragma("unroll") for (int k = 0; k < 2; ++k) dst[n][k] = *(const PG8_LAS bf16x8*)(lds + PG8_SB(b, h) + boff + n * 2048 + k * 1024); } while (0)
; #define PG8_MMA(ai, bj, At, Bt) do { __builtin_amdgcn_s_setprio(1); _Pragma("unroll") for (int m = 0; m < 4; ++m) _Pragma("unroll") for (int n = 0; n < 2; ++n) _Pragma("unroll") for (int k = 0; k < 2; ++k) \
;         acc[ai][bj][m][n] = __builtin_amdgcn_mfma_f32_16x16x32_bf16(Bt[n][k], At[m][k], acc[ai][bj][m][n], 0, 0, 0); __builtin_amdgcn_s_setprio(0); } while (0)
; #define PG8_WAIT_V(n) asm volatile("s_waitcnt vmcnt(" #n ")" ::: "memory")
; #define PG8_WAIT_L(n) asm volatile("s_waitcnt lgkmcnt(" #n ")" ::: "memory")
; #define PG8_BAR __builtin_amdgcn_s_barrier()
; #define PG8_SCHED __builtin_amdgcn_sched_barrier(0)
; template <class Epi, class Sched, bool ALIGN_EPI = false, bool SP2 = false>
; __device__ __forceinline__ void gemm_phase(PG8_LAS unsigned char* lds, const Gemm g, const Sched& S, const Epi& E) {
;     ...
;             PG8_WAIT_V(8); PG8_WAIT_L(0); PG8_BAR; PG8_MMA(1, 0, At, B0); PG8_MMA(1, 1, At, B1); PG8_BAR; PG8_SCHED;
;             PG8_LDB(B0, 1, 0); PG8_LDB(B1, 1, 1); PG8_SCHED; PG8_LDA(At, 1, 0); PG8_STAGE(PG8_SA(0, 1), a2 + hstep, voffA);
;             PG8_WAIT_V(8); PG8_WAIT_L(0); PG8_BAR; PG8_MMA(0, 0, At, B0); PG8_MMA(0, 1, At, B1); PG8_BAR; PG8_SCHED;
	s_setprio 1
	s_waitcnt lgkmcnt(0)
	v_mfma_f32_16x16x32_bf16 v[110:113], v[26:29], v[178:181], v[110:113]
	v_mfma_f32_16x16x32_bf16 v[110:113], v[30:33], v[182:185], v[110:113]
	v_mfma_f32_16x16x32_bf16 v[94:97], v[26:29], v[186:189], v[94:97]
	v_mfma_f32_16x16x32_bf16 v[94:97], v[30:33], v[190:193], v[94:97]
	v_mfma_f32_16x16x32_bf16 v[86:89], v[26:29], v[194:197], v[86:89]
	v_mfma_f32_16x16x32_bf16 v[86:89], v[30:33], v[198:201], v[86:89]
	v_mfma_f32_16x16x32_bf16 v[26:29], v[26:29], v[202:205], v[78:81]
	v_mfma_f32_16x16x32_bf16 v[26:29], v[30:33], v[212:215], v[26:29]
	v_mfma_f32_16x16x32_bf16 v[106:109], v[98:101], v[178:181], v[106:109]
	v_mfma_f32_16x16x32_bf16 v[106:109], v[102:105], v[182:185], v[106:109]
	v_mfma_f32_16x16x32_bf16 v[90:93], v[98:101], v[186:189], v[90:93]
	v_mfma_f32_16x16x32_bf16 v[90:93], v[102:105], v[190:193], v[90:93]
	v_mfma_f32_16x16x32_bf16 v[82:85], v[98:101], v[194:197], v[82:85]
	v_mfma_f32_16x16x32_bf16 v[82:85], v[102:105], v[198:201], v[82:85]
	v_mfma_f32_16x16x32_bf16 v[30:33], v[98:101], v[202:205], v[74:77]
	v_mfma_f32_16x16x32_bf16 v[30:33], v[102:105], v[212:215], v[30:33]
	s_setprio 0
	s_setprio 1
	v_mfma_f32_16x16x32_bf16 v[38:41], v[146:149], v[178:181], v[38:41]
	v_mfma_f32_16x16x32_bf16 v[38:41], v[150:153], v[182:185], v[38:41]
	v_mfma_f32_16x16x32_bf16 v[22:25], v[146:149], v[186:189], v[22:25]
	v_mfma_f32_16x16x32_bf16 v[22:25], v[150:153], v[190:193], v[22:25]
	v_mfma_f32_16x16x32_bf16 v[14:17], v[146:149], v[194:197], v[14:17]
	v_mfma_f32_16x16x32_bf16 v[14:17], v[150:153], v[198:201], v[14:17]
	v_mfma_f32_16x16x32_bf16 v[6:9], v[146:149], v[202:205], v[6:9]
	v_mfma_f32_16x16x32_bf16 v[6:9], v[150:153], v[212:215], v[6:9]
	v_mfma_f32_16x16x32_bf16 v[34:37], v[154:157], v[178:181], v[34:37]
	v_mfma_f32_16x16x32_bf16 v[34:37], v[158:161], v[182:185], v[34:37]
	v_mfma_f32_16x16x32_bf16 v[18:21], v[154:157], v[186:189], v[18:21]
	v_mfma_f32_16x16x32_bf16 v[18:21], v[158:161], v[190:193], v[18:21]
	v_mfma_f32_16x16x32_bf16 v[10:13], v[154:157], v[194:197], v[10:13]
	v_mfma_f32_16x16x32_bf16 v[10:13], v[158:161], v[198:201], v[10:13]
	v_mfma_f32_16x16x32_bf16 v[2:5], v[154:157], v[202:205], v[2:5]
	v_mfma_f32_16x16x32_bf16 v[2:5], v[158:161], v[212:215], v[2:5]
	s_setprio 0
	s_barrier
	s_add_i32 s56, 0, 0x18000
	s_add_i32 s57, 0, 0x1c000
	v_add_u32_e32 v102, s56, v208
	v_add_u32_e32 v158, s57, v208
	ds_read_b128 v[74:77], v102
	ds_read_b128 v[78:81], v102 offset:1024
	ds_read_b128 v[98:101], v102 offset:2048
	ds_read_b128 v[102:105], v102 offset:3072
	ds_read_b128 v[146:149], v158
	ds_read_b128 v[150:153], v158 offset:1024
	ds_read_b128 v[154:157], v158 offset:2048
	ds_read_b128 v[158:161], v158 offset:3072
	s_add_u32 s4, s12, 0x80000
	s_addc_u32 s5, s13, 0
	v_mov_b32_e32 v211, v1
	s_mov_b32 m0, s20
	ds_read_b128 v[178:181], v210 offset:32768
	ds_read_b128 v[182:185], v210 offset:33792
	ds_read_b128 v[186:189], v210 offset:34816
	ds_read_b128 v[190:193], v210 offset:35840
	ds_read_b128 v[194:197], v210 offset:36864
	ds_read_b128 v[198:201], v210 offset:37888
	ds_read_b128 v[202:205], v210 offset:38912
	ds_read_b128 v[212:215], v210 offset:39936
	s_nop 0
	global_load_lds_dwordx4 v211, s[4:5]
	v_mov_b32_e32 v211, v164
	s_mov_b32 m0, s21
	s_nop 0
	global_load_lds_dwordx4 v211, s[4:5]
	s_waitcnt vmcnt(8)
	s_waitcnt lgkmcnt(0)
	s_barrier
	s_setprio 1
	s_waitcnt lgkmcnt(0)
	v_mfma_f32_16x16x32_bf16 v[142:145], v[74:77], v[178:181], v[142:145]
	v_mfma_f32_16x16x32_bf16 v[142:145], v[78:81], v[182:185], v[142:145]
	v_mfma_f32_16x16x32_bf16 v[134:137], v[74:77], v[186:189], v[134:137]
	v_mfma_f32_16x16x32_bf16 v[134:137], v[78:81], v[190:193], v[134:137]
	v_mfma_f32_16x16x32_bf16 v[126:129], v[74:77], v[194:197], v[126:129]
	v_mfma_f32_16x16x32_bf16 v[126:129], v[78:81], v[198:201], v[126:129]
	v_mfma_f32_16x16x32_bf16 v[118:121], v[74:77], v[202:205], v[118:121]
	v_mfma_f32_16x16x32_bf16 v[118:121], v[78:81], v[212:215], v[118:121]
	v_mfma_f32_16x16x32_bf16 v[138:141], v[98:101], v[178:181], v[138:141]
	v_mfma_f32_16x16x32_bf16 v[138:141], v[102:105], v[182:185], v[138:141]
	v_mfma_f32_16x16x32_bf16 v[130:133], v[98:101], v[186:189], v[130:133]
	v_mfma_f32_16x16x32_bf16 v[130:133], v[102:105], v[190:193], v[130:133]
	v_mfma_f32_16x16x32_bf16 v[122:125], v[98:101], v[194:197], v[122:125]
	v_mfma_f32_16x16x32_bf16 v[122:125], v[102:105], v[198:201], v[122:125]
	v_mfma_f32_16x16x32_bf16 v[114:117], v[98:101], v[202:205], v[114:117]
	v_mfma_f32_16x16x32_bf16 v[114:117], v[102:105], v[212:215], v[114:117]
	s_setprio 0
	s_setprio 1
	v_mfma_f32_16x16x32_bf16 v[70:73], v[146:149], v[178:181], v[70:73]
	v_mfma_f32_16x16x32_bf16 v[70:73], v[150:153], v[182:185], v[70:73]
	v_mfma_f32_16x16x32_bf16 v[62:65], v[146:149], v[186:189], v[62:65]
	v_mfma_f32_16x16x32_bf16 v[62:65], v[150:153], v[190:193], v[62:65]
	v_mfma_f32_16x16x32_bf16 v[54:57], v[146:149], v[194:197], v[54:57]
	v_mfma_f32_16x16x32_bf16 v[54:57], v[150:153], v[198:201], v[54:57]
	v_mfma_f32_16x16x32_bf16 v[46:49], v[146:149], v[202:205], v[46:49]
	v_mfma_f32_16x16x32_bf16 v[46:49], v[150:153], v[212:215], v[46:49]
	v_mfma_f32_16x16x32_bf16 v[66:69], v[154:157], v[178:181], v[66:69]
	v_mfma_f32_16x16x32_bf16 v[66:69], v[158:161], v[182:185], v[66:69]
	v_mfma_f32_16x16x32_bf16 v[58:61], v[154:157], v[186:189], v[58:61]
	v_mfma_f32_16x16x32_bf16 v[58:61], v[158:161], v[190:193], v[58:61]
	v_mfma_f32_16x16x32_bf16 v[50:53], v[154:157], v[194:197], v[50:53]
	v_mfma_f32_16x16x32_bf16 v[50:53], v[158:161], v[198:201], v[50:53]
	v_mfma_f32_16x16x32_bf16 v[42:45], v[154:157], v[202:205], v[42:45]
	v_mfma_f32_16x16x32_bf16 v[42:45], v[158:161], v[212:215], v[42:45]
	s_setprio 0
	s_barrier
;     __device__ __forceinline__ void operator()(const f32x4 (&acc)[2][2][4][2], const Unit& u, int wr, int wc, int fr, int fq) const {
;         const int row0 = u.pm * BM + wr * 64 + fr, col0 = u.pn * BM + wc * 32 + 8 * fq, b = (u.pm * BM) / rows_per_batch;
;         const float* g = gate + (size_t)b * gate_bstride + col0;
;         float ssq[2][4];
; #pragma unroll
;         for (int ai = 0; ai < 2; ++ai)
; #pragma unroll
;             for (int m = 0; m < 4; ++m) ssq[ai][m] = 0.f;
;         f32x4 gv[2][2], Gv[2][2];
; #pragma unroll
;         for (int bj = 0; bj < 2; ++bj) { gv[bj][0] = *(const f32x4*)(g + bj * HALF); gv[bj][1] = *(const f32x4*)(g + bj * HALF + 4); Gv[bj][0] = (f32x4){0.f, 0.f, 0.f, 0.f}; Gv[bj][1] = (f32x4){0.f, 0.f, 0.f, 0.f};
;             if (Hn) { const float* sc = scnext + (size_t)b * gate_bstride + col0 + bj * HALF;
;                 Gv[bj][0] = *(const f32x4*)(gnext + col0 + bj * HALF) * (1.0f + *(const f32x4*)(sc)); Gv[bj][1] = *(const f32x4*)(gnext + col0 + bj * HALF + 4) * (1.0f + *(const f32x4*)(sc + 4)); } }
; #pragma unroll
;         for (int bj = 0; bj < 2; ++bj) {
;             const f32x4 g0 = gv[bj][0], g1 = gv[bj][1], G0 = Gv[bj][0], G1 = Gv[bj][1];
; #pragma unroll
;             for (int ai = 0; ai < 2; ++ai)
; #pragma unroll
;                 for (int m = 0; m < 4; ++m) { const size_t off = (size_t)(row0 + ai * HALF + m * 16) * 2048 + col0 + bj * HALF;
;                     f32x4 x0 = __builtin_nontemporal_load((const f32x4*)(base + off)), x1 = __builtin_nontemporal_load((const f32x4*)(base + off + 4));
;                     if constexpr (HAS_DIN) { const u32x4 dw = __builtin_nontemporal_load((const u32x4*)(dbuf + off));
;                         x0 += (f32x4){__builtin_bit_cast(float, dw.x << 16), __builtin_bit_cast(float, dw.x & 0xffff0000u), __builtin_bit_cast(float, dw.y << 16), __builtin_bit_cast(float, dw.y & 0xffff0000u)};
; template <class Epi, class Sched, bool ALIGN_EPI = false, bool SP2 = false>
; __device__ __forceinline__ void gemm_phase(PG8_LAS unsigned char* lds, const Gemm g, const Sched& S, const Epi& E) {
;     ...
;             PG8_LDA(At, 1, 1); PG8_STAGE(PG8_SB(1, 0), b3, voffB); PG8_STAGE(PG8_SB(1, 1), b3 + hstep, voffB); PG8_STAGE(PG8_SA(1, 0), a3, voffA);
;             PG8_WAIT_V(8); PG8_WAIT_L(0); PG8_BAR; PG8_MMA(1, 0, At, B0); PG8_MMA(1, 1, At, B1); PG8_BAR; PG8_SCHED;
	s_add_u32 s4, s10, 0x80
	s_addc_u32 s5, s11, 0
	v_mov_b32_e32 v211, v162
	s_add_i32 s12, s56, s17
	ds_read_b128 v[178:181], v210 offset:49152
	ds_read_b128 v[182:185], v210 offset:50176
	ds_read_b128 v[186:189], v210 offset:51200
	ds_read_b128 v[190:193], v210 offset:52224
	ds_read_b128 v[194:197], v210 offset:53248
	ds_read_b128 v[198:201], v210 offset:54272
	ds_read_b128 v[202:205], v210 offset:55296
	ds_read_b128 v[212:215], v210 offset:56320
	s_mov_b32 m0, s12
	s_nop 0
	global_load_lds_dwordx4 v211, s[4:5]
	v_mov_b32_e32 v211, v206
	s_add_i32 m0, s12, 0x2000
	s_nop 0
	global_load_lds_dwordx4 v211, s[4:5]
	s_add_u32 s4, s10, 0x80080
	s_addc_u32 s5, s11, 0
	v_mov_b32_e32 v211, v162
	s_add_i32 s10, s57, s17
	s_mov_b32 m0, s10
	s_nop 0
	global_load_lds_dwordx4 v211, s[4:5]
	v_mov_b32_e32 v211, v206
	s_add_i32 m0, s10, 0x2000
	s_nop 0
	global_load_lds_dwordx4 v211, s[4:5]
	v_mov_b32_e32 v211, v1
	s_mov_b32 m0, s26
	s_nop 0
	global_load_lds_dwordx4 v211, s[8:9]
	v_mov_b32_e32 v211, v164
	s_mov_b32 m0, s27
	s_nop 0
	global_load_lds_dwordx4 v211, s[8:9]
	s_waitcnt vmcnt(8)
	s_waitcnt lgkmcnt(0)
	s_barrier
	s_setprio 1
	s_waitcnt lgkmcnt(0)
	v_mfma_f32_16x16x32_bf16 v[110:113], v[74:77], v[178:181], v[110:113]
	v_mfma_f32_16x16x32_bf16 v[110:113], v[78:81], v[182:185], v[110:113]
	v_mfma_f32_16x16x32_bf16 v[94:97], v[74:77], v[186:189], v[94:97]
	v_mfma_f32_16x16x32_bf16 v[94:97], v[78:81], v[190:193], v[94:97]
	v_mfma_f32_16x16x32_bf16 v[86:89], v[74:77], v[194:197], v[86:89]
	v_mfma_f32_16x16x32_bf16 v[86:89], v[78:81], v[198:201], v[86:89]
	v_mfma_f32_16x16x32_bf16 v[26:29], v[74:77], v[202:205], v[26:29]
	v_mfma_f32_16x16x32_bf16 v[78:81], v[78:81], v[212:215], v[26:29]
	v_mfma_f32_16x16x32_bf16 v[106:109], v[98:101], v[178:181], v[106:109]
	v_mfma_f32_16x16x32_bf16 v[106:109], v[102:105], v[182:185], v[106:109]
	v_mfma_f32_16x16x32_bf16 v[90:93], v[98:101], v[186:189], v[90:93]
	v_mfma_f32_16x16x32_bf16 v[90:93], v[102:105], v[190:193], v[90:93]
	v_mfma_f32_16x16x32_bf16 v[82:85], v[98:101], v[194:197], v[82:85]
	v_mfma_f32_16x16x32_bf16 v[82:85], v[102:105], v[198:201], v[82:85]
	v_mfma_f32_16x16x32_bf16 v[26:29], v[98:101], v[202:205], v[30:33]
	v_mfma_f32_16x16x32_bf16 v[74:77], v[102:105], v[212:215], v[26:29]
	s_setprio 0
	s_setprio 1
	v_mfma_f32_16x16x32_bf16 v[26:29], v[146:149], v[178:181], v[38:41]
	v_mfma_f32_16x16x32_bf16 v[38:41], v[150:153], v[182:185], v[26:29]
	v_mfma_f32_16x16x32_bf16 v[22:25], v[146:149], v[186:189], v[22:25]
	v_mfma_f32_16x16x32_bf16 v[22:25], v[150:153], v[190:193], v[22:25]
	v_mfma_f32_16x16x32_bf16 v[14:17], v[146:149], v[194:197], v[14:17]
	v_mfma_f32_16x16x32_bf16 v[14:17], v[150:153], v[198:201], v[14:17]
	v_mfma_f32_16x16x32_bf16 v[6:9], v[146:149], v[202:205], v[6:9]
	v_mfma_f32_16x16x32_bf16 v[6:9], v[150:153], v[212:215], v[6:9]
	v_mfma_f32_16x16x32_bf16 v[26:29], v[154:157], v[178:181], v[34:37]
	v_mfma_f32_16x16x32_bf16 v[34:37], v[158:161], v[182:185], v[26:29]
	v_mfma_f32_16x16x32_bf16 v[18:21], v[154:157], v[186:189], v[18:21]
	v_mfma_f32_16x16x32_bf16 v[18:21], v[158:161], v[190:193], v[18:21]
	v_mfma_f32_16x16x32_bf16 v[10:13], v[154:157], v[194:197], v[10:13]
	v_mfma_f32_16x16x32_bf16 v[10:13], v[158:161], v[198:201], v[10:13]
	v_mfma_f32_16x16x32_bf16 v[2:5], v[154:157], v[202:205], v[2:5]
	v_mfma_f32_16x16x32_bf16 v[2:5], v[158:161], v[212:215], v[2:5]
	s_setprio 0
	s_barrier
	s_add_i32 s51, s51, 2
	s_add_u32 s40, s40, 0x100
	s_addc_u32 s49, s49, 0
	s_cmp_gt_u32 s51, 29
	s_mov_b64 s[4:5], s[6:7]
	s_cbranch_scc0 .LBB0_555
	s_ashr_i32 s4, s29, 31
	s_lshr_b32 s4, s4, 27
	s_add_i32 s4, s29, s4
	s_ashr_i32 s4, s4, 5
	v_lshl_or_b32 v148, s33, 8, v209
	s_mul_i32 s7, s4, 0xc000
	v_ashrrev_i32_e32 v149, 31, v148
	s_mul_hi_i32 s6, s4, 0xc000
	s_add_u32 s4, s22, s7
	s_addc_u32 s5, s23, s6
	v_lshlrev_b64 v[26:27], 2, v[148:149]
	v_lshl_add_u64 v[146:147], s[4:5], 0, v[26:27]
	s_add_u32 s4, s24, s7
	s_addc_u32 s5, s25, s6
	v_lshl_add_u64 v[160:161], s[4:5], 0, v[26:27]
	v_lshl_add_u64 v[178:179], s[46:47], 0, v[26:27]
	global_load_dwordx4 v[98:101], v[146:147], off offset:16
	global_load_dwordx4 v[102:105], v[146:147], off
	global_load_dwordx4 v[26:29], v[178:179], off offset:16
	global_load_dwordx4 v[30:33], v[178:179], off
	global_load_dwordx4 v[150:153], v[160:161], off offset:16
	global_load_dwordx4 v[154:157], v[160:161], off
	s_mov_b64 s[4:5], 0x40000
	s_waitcnt vmcnt(0)
	v_pk_mul_f32 v[188:189], v[140:141], v[100:101]
	v_pk_mul_f32 v[142:143], v[142:143], v[102:103]
	v_pk_mul_f32 v[144:145], v[144:145], v[104:105]
	v_pk_mul_f32 v[140:141], v[138:139], v[98:99]
	v_pk_mul_f32 v[136:137], v[136:137], v[104:105]
	v_pk_add_f32 v[156:157], v[156:157], 1.0 op_sel_hi:[1,0]
	v_pk_add_f32 v[154:155], v[154:155], 1.0 op_sel_hi:[1,0]
	v_pk_mul_f32 v[198:199], v[32:33], v[156:157]
	v_pk_mul_f32 v[200:201], v[30:31], v[154:155]
	v_pk_add_f32 v[30:31], v[152:153], 1.0 op_sel_hi:[1,0]
	v_pk_add_f32 v[32:33], v[150:151], 1.0 op_sel_hi:[1,0]
	v_pk_mul_f32 v[202:203], v[28:29], v[30:31]
	v_pk_mul_f32 v[204:205], v[26:27], v[32:33]
	global_load_dwordx4 v[26:29], v[146:147], off offset:528
	global_load_dwordx4 v[30:33], v[146:147], off offset:512
	global_load_dwordx4 v[156:159], v[178:179], off offset:528
	global_load_dwordx4 v[152:155], v[178:179], off offset:512
	s_nop 0
	global_load_dwordx4 v[178:181], v[160:161], off offset:528
	global_load_dwordx4 v[182:185], v[160:161], off offset:512
	v_pk_mul_f32 v[134:135], v[134:135], v[102:103]
	v_pk_mul_f32 v[130:131], v[130:131], v[98:99]
	v_pk_mul_f32 v[132:133], v[132:133], v[100:101]
	v_pk_mul_f32 v[128:129], v[128:129], v[104:105]
	v_pk_mul_f32 v[126:127], v[126:127], v[102:103]
	v_pk_mul_f32 v[122:123], v[122:123], v[98:99]
	v_pk_mul_f32 v[124:125], v[124:125], v[100:101]
	v_pk_mul_f32 v[120:121], v[120:121], v[104:105]
	v_pk_mul_f32 v[118:119], v[118:119], v[102:103]
	v_pk_mul_f32 v[114:115], v[114:115], v[98:99]
	v_pk_mul_f32 v[116:117], v[116:117], v[100:101]
	v_pk_mul_f32 v[112:113], v[112:113], v[104:105]
	v_pk_mul_f32 v[110:111], v[110:111], v[102:103]
	v_pk_mul_f32 v[106:107], v[106:107], v[98:99]
	v_pk_mul_f32 v[108:109], v[108:109], v[100:101]
	v_pk_mul_f32 v[96:97], v[96:97], v[104:105]
	v_pk_mul_f32 v[94:95], v[94:95], v[102:103]
	v_pk_mul_f32 v[90:91], v[90:91], v[98:99]
	v_pk_mul_f32 v[92:93], v[92:93], v[100:101]
	v_pk_mul_f32 v[88:89], v[88:89], v[104:105]
	v_pk_mul_f32 v[86:87], v[86:87], v[102:103]
	v_pk_mul_f32 v[82:83], v[82:83], v[98:99]
	v_pk_mul_f32 v[84:85], v[84:85], v[100:101]
	v_pk_mul_f32 v[80:81], v[80:81], v[104:105]
	v_pk_mul_f32 v[78:79], v[78:79], v[102:103]
	v_pk_mul_f32 v[74:75], v[74:75], v[98:99]
	v_pk_mul_f32 v[76:77], v[76:77], v[100:101]
	s_waitcnt vmcnt(5)
; __device__ __forceinline__ unsigned cvt_pk_bf16(float lo, float hi) { unsigned r; asm volatile("v_cvt_pk_bf16_f32 %0, %1, %2" : "=v"(r) : "v"(lo), "v"(hi)); return r; }
;     __device__ __forceinline__ void operator()(const f32x4 (&acc)[2][2][4][2], const Unit& u, int wr, int wc, int fr, int fq) const {
;     ...
;                 for (int m = 0; m < 4; ++m) { const size_t off = (size_t)(row0 + ai * HALF + m * 16) * 2048 + col0 + bj * HALF;
;                     f32x4 x0 = __builtin_nontemporal_load((const f32x4*)(base + off)), x1 = __builtin_nontemporal_load((const f32x4*)(base + off + 4));
;                     if constexpr (HAS_DIN) { const u32x4 dw = __builtin_nontemporal_load((const u32x4*)(dbuf + off));
;                         x0 += (f32x4){__builtin_bit_cast(float, dw.x << 16), __builtin_bit_cast(float, dw.x & 0xffff0000u), __builtin_bit_cast(float, dw.y << 16), __builtin_bit_cast(float, dw.y & 0xffff0000u)};
;                         x1 += (f32x4){__builtin_bit_cast(float, dw.z << 16), __builtin_bit_cast(float, dw.z & 0xffff0000u), __builtin_bit_cast(float, dw.w << 16), __builtin_bit_cast(float, dw.w & 0xffff0000u)}; }
;                     f32x4 o0, o1;
;                     if constexpr (OUT_DELTA) { const f32x4 d0 = g0 * acc[ai][bj][m][0], d1 = g1 * acc[ai][bj][m][1];
;                         u32x4 w; w.x = cvt_pk_bf16(d0[0], d0[1]); w.y = cvt_pk_bf16(d0[2], d0[3]); w.z = cvt_pk_bf16(d1[0], d1[1]); w.w = cvt_pk_bf16(d1[2], d1[3]);
;                         *(u32x4*)(dbuf + off) = w;
;                         o0 = x0 + (f32x4){__builtin_bit_cast(float, w.x << 16), __builtin_bit_cast(float, w.x & 0xffff0000u), __builtin_bit_cast(float, w.y << 16), __builtin_bit_cast(float, w.y & 0xffff0000u)};
;                         o1 = x1 + (f32x4){__builtin_bit_cast(float, w.z << 16), __builtin_bit_cast(float, w.z & 0xffff0000u), __builtin_bit_cast(float, w.w << 16), __builtin_bit_cast(float, w.w & 0xffff0000u)}; }
;                     else { o0 = x0 + g0 * acc[ai][bj][m][0]; o1 = x1 + g1 * acc[ai][bj][m][1]; *(f32x4*)(out + off) = o0; *(f32x4*)(out + off + 4) = o1; }
;                     if (Hn) { const f32x4 h0 = o0 * G0, h1 = o1 * G1;
;                         u32x4 w; w.x = cvt_pk_bf16(h0[0], h0[1]); w.y = cvt_pk_bf16(h0[2], h0[3]); w.z = cvt_pk_bf16(h1[0], h1[1]); w.w = cvt_pk_bf16(h1[2], h1[3]);
;                         *(u32x4*)(Hn + off) = w;
	v_pk_mul_f32 v[58:59], v[58:59], v[26:27]
	s_waitcnt vmcnt(4)
	v_pk_mul_f32 v[72:73], v[72:73], v[32:33]
	v_pk_mul_f32 v[70:71], v[70:71], v[30:31]
	v_pk_mul_f32 v[64:65], v[64:65], v[32:33]
	v_pk_mul_f32 v[62:63], v[62:63], v[30:31]
	s_waitcnt vmcnt(0)
	v_pk_add_f32 v[146:147], v[184:185], 1.0 op_sel_hi:[1,0]
	v_pk_add_f32 v[160:161], v[182:183], 1.0 op_sel_hi:[1,0]
	v_pk_mul_f32 v[150:151], v[154:155], v[146:147]
	v_pk_add_f32 v[146:147], v[180:181], 1.0 op_sel_hi:[1,0]
	v_pk_mul_f32 v[152:153], v[152:153], v[160:161]
	v_pk_mul_f32 v[154:155], v[158:159], v[146:147]
	v_lshl_add_u32 v146, s29, 8, v207
	v_ashrrev_i32_e32 v147, 31, v146
	v_lshlrev_b64 v[184:185], 11, v[146:147]
	v_lshl_add_u64 v[186:187], v[184:185], 0, v[148:149]
	v_pk_add_f32 v[160:161], v[178:179], 1.0 op_sel_hi:[1,0]
	v_lshl_add_u64 v[178:179], v[186:187], 2, s[44:45]
	v_pk_mul_f32 v[156:157], v[156:157], v[160:161]
	global_load_dwordx4 v[158:161], v[178:179], off nt
	global_load_dwordx4 v[180:183], v[178:179], off offset:16 nt
	v_cvt_pk_bf16_f32 v138, v142, v143
	v_lshlrev_b64 v[142:143], 1, v[186:187]
	v_cvt_pk_bf16_f32 v139, v144, v145
	v_cvt_pk_bf16_f32 v140, v140, v141
	v_cvt_pk_bf16_f32 v141, v188, v189
	v_lshl_add_u64 v[144:145], s[90:91], 0, v[142:143]
	global_store_dwordx4 v[144:145], v[138:141], off
	v_lshlrev_b32_e32 v144, 16, v140
	v_and_b32_e32 v145, 0xffff0000, v140
	v_lshlrev_b32_e32 v140, 16, v141
	v_and_b32_e32 v141, 0xffff0000, v141
	v_lshl_add_u64 v[142:143], s[96:97], 0, v[142:143]
	v_pk_mul_f32 v[60:61], v[60:61], v[28:29]
	v_pk_mul_f32 v[56:57], v[56:57], v[32:33]
	v_pk_mul_f32 v[54:55], v[54:55], v[30:31]
	v_pk_mul_f32 v[50:51], v[50:51], v[26:27]
	v_pk_mul_f32 v[52:53], v[52:53], v[28:29]
	v_pk_mul_f32 v[48:49], v[48:49], v[32:33]
	v_pk_mul_f32 v[46:47], v[46:47], v[30:31]
	v_pk_mul_f32 v[42:43], v[42:43], v[26:27]
	v_pk_mul_f32 v[44:45], v[44:45], v[28:29]
	v_pk_mul_f32 v[40:41], v[40:41], v[32:33]
	v_pk_mul_f32 v[38:39], v[38:39], v[30:31]
	v_pk_mul_f32 v[34:35], v[34:35], v[26:27]
	v_pk_mul_f32 v[36:37], v[36:37], v[28:29]
	v_pk_mul_f32 v[24:25], v[24:25], v[32:33]
	v_pk_mul_f32 v[22:23], v[22:23], v[30:31]
	v_pk_mul_f32 v[18:19], v[18:19], v[26:27]
	v_pk_mul_f32 v[20:21], v[20:21], v[28:29]
	v_pk_mul_f32 v[16:17], v[16:17], v[32:33]
	v_pk_mul_f32 v[14:15], v[14:15], v[30:31]
	v_pk_mul_f32 v[10:11], v[10:11], v[26:27]
	v_pk_mul_f32 v[12:13], v[12:13], v[28:29]
	v_pk_mul_f32 v[8:9], v[8:9], v[32:33]
	v_pk_mul_f32 v[6:7], v[6:7], v[30:31]
	v_pk_mul_f32 v[2:3], v[2:3], v[26:27]
	v_pk_mul_f32 v[4:5], v[4:5], v[28:29]
	s_waitcnt vmcnt(1)
	v_pk_add_f32 v[182:183], v[182:183], v[140:141]
	v_lshlrev_b32_e32 v140, 16, v138
	v_and_b32_e32 v141, 0xffff0000, v138
	v_lshlrev_b32_e32 v138, 16, v139
	v_and_b32_e32 v139, 0xffff0000, v139
	v_pk_add_f32 v[158:159], v[158:159], v[140:141]
	v_pk_add_f32 v[160:161], v[160:161], v[138:139]
	v_pk_mul_f32 v[138:139], v[200:201], v[158:159]
	v_pk_add_f32 v[144:145], v[180:181], v[144:145]
	v_pk_mul_f32 v[140:141], v[198:199], v[160:161]
	v_cvt_pk_bf16_f32 v138, v138, v139
	v_pk_mul_f32 v[180:181], v[202:203], v[182:183]
	v_cvt_pk_bf16_f32 v139, v140, v141
	v_pk_mul_f32 v[186:187], v[204:205], v[144:145]
	s_nop 0
	v_cvt_pk_bf16_f32 v140, v186, v187
	v_cvt_pk_bf16_f32 v141, v180, v181
	global_store_dwordx4 v[142:143], v[138:141], off
	s_nop 1
	v_mul_f32_e32 v138, v159, v159
	v_mul_f32_e32 v139, v161, v161
	v_fmac_f32_e32 v138, v158, v158
	v_fmac_f32_e32 v139, v160, v160
	v_add_f32_e32 v138, v138, v139
	v_mul_f32_e32 v139, v145, v145
	v_mul_f32_e32 v140, v183, v183
	v_fmac_f32_e32 v139, v144, v144
	v_fmac_f32_e32 v140, v182, v182
	v_add_f32_e32 v139, v139, v140
	v_add_f32_e32 v211, v138, v139
	v_or_b32_e32 v138, 16, v146
	v_ashrrev_i32_e32 v139, 31, v138
	v_lshlrev_b64 v[140:141], 11, v[138:139]
	v_lshl_add_u64 v[180:181], v[140:141], 0, v[148:149]
	v_lshl_add_u64 v[138:139], v[180:181], 2, s[44:45]
	global_load_dwordx4 v[142:145], v[138:139], off nt
	global_load_dwordx4 v[158:161], v[138:139], off offset:16 nt
	v_lshlrev_b64 v[180:181], 1, v[180:181]
	v_cvt_pk_bf16_f32 v134, v134, v135
	v_cvt_pk_bf16_f32 v135, v136, v137
	v_cvt_pk_bf16_f32 v136, v130, v131
	v_cvt_pk_bf16_f32 v137, v132, v133
	v_lshl_add_u64 v[130:131], s[90:91], 0, v[180:181]
	global_store_dwordx4 v[130:131], v[134:137], off
	v_lshlrev_b32_e32 v132, 16, v136
	v_and_b32_e32 v133, 0xffff0000, v136
	v_lshlrev_b32_e32 v130, 16, v137
	v_and_b32_e32 v131, 0xffff0000, v137
	v_lshlrev_b32_e32 v136, 16, v134
	v_and_b32_e32 v137, 0xffff0000, v134
	v_lshlrev_b32_e32 v134, 16, v135
	v_and_b32_e32 v135, 0xffff0000, v135
	s_waitcnt vmcnt(2)
	v_pk_add_f32 v[134:135], v[144:145], v[134:135]
	s_waitcnt vmcnt(1)
	v_pk_add_f32 v[130:131], v[160:161], v[130:131]
	v_pk_add_f32 v[136:137], v[142:143], v[136:137]
	v_pk_add_f32 v[132:133], v[158:159], v[132:133]
	v_pk_mul_f32 v[144:145], v[198:199], v[134:135]
	v_pk_mul_f32 v[142:143], v[200:201], v[136:137]
	v_pk_mul_f32 v[158:159], v[202:203], v[130:131]
	v_pk_mul_f32 v[160:161], v[204:205], v[132:133]
	v_cvt_pk_bf16_f32 v142, v142, v143
	v_cvt_pk_bf16_f32 v143, v144, v145
	s_nop 0
	v_cvt_pk_bf16_f32 v144, v160, v161
	v_cvt_pk_bf16_f32 v145, v158, v159
	v_lshl_add_u64 v[158:159], s[96:97], 0, v[180:181]
	global_store_dwordx4 v[158:159], v[142:145], off
	s_nop 1
	v_or_b32_e32 v142, 32, v146
	v_ashrrev_i32_e32 v143, 31, v142
	v_lshlrev_b64 v[144:145], 11, v[142:143]
	v_lshl_add_u64 v[186:187], v[144:145], 0, v[148:149]
	v_lshl_add_u64 v[142:143], v[186:187], 2, s[44:45]
	global_load_dwordx4 v[158:161], v[142:143], off nt
	global_load_dwordx4 v[180:183], v[142:143], off offset:16 nt
	v_lshlrev_b64 v[186:187], 1, v[186:187]
	v_cvt_pk_bf16_f32 v126, v126, v127
	v_cvt_pk_bf16_f32 v127, v128, v129
	v_cvt_pk_bf16_f32 v128, v122, v123
	v_cvt_pk_bf16_f32 v129, v124, v125
	v_lshl_add_u64 v[122:123], s[90:91], 0, v[186:187]
	global_store_dwordx4 v[122:123], v[126:129], off
	v_lshlrev_b32_e32 v124, 16, v128
	v_and_b32_e32 v125, 0xffff0000, v128
	v_lshlrev_b32_e32 v122, 16, v129
	v_and_b32_e32 v123, 0xffff0000, v129
	v_lshlrev_b32_e32 v128, 16, v126
	v_and_b32_e32 v129, 0xffff0000, v126
	v_lshlrev_b32_e32 v126, 16, v127
	v_and_b32_e32 v127, 0xffff0000, v127
	s_waitcnt vmcnt(2)
; __device__ __forceinline__ unsigned cvt_pk_bf16(float lo, float hi) { unsigned r; asm volatile("v_cvt_pk_bf16_f32 %0, %1, %2" : "=v"(r) : "v"(lo), "v"(hi)); return r; }
;     __device__ __forceinline__ void operator()(const f32x4 (&acc)[2][2][4][2], const Unit& u, int wr, int wc, int fr, int fq) const {
;     ...
;                 for (int m = 0; m < 4; ++m) { const size_t off = (size_t)(row0 + ai * HALF + m * 16) * 2048 + col0 + bj * HALF;
;                     f32x4 x0 = __builtin_nontemporal_load((const f32x4*)(base + off)), x1 = __builtin_nontemporal_load((const f32x4*)(base + off + 4));
;                     if constexpr (HAS_DIN) { const u32x4 dw = __builtin_nontemporal_load((const u32x4*)(dbuf + off));
;                         x0 += (f32x4){__builtin_bit_cast(float, dw.x << 16), __builtin_bit_cast(float, dw.x & 0xffff0000u), __builtin_bit_cast(float, dw.y << 16), __builtin_bit_cast(float, dw.y & 0xffff0000u)};
;                         x1 += (f32x4){__builtin_bit_cast(float, dw.z << 16), __builtin_bit_cast(float, dw.z & 0xffff0000u), __builtin_bit_cast(float, dw.w << 16), __builtin_bit_cast(float, dw.w & 0xffff0000u)}; }
;                     f32x4 o0, o1;
;                     if constexpr (OUT_DELTA) { const f32x4 d0 = g0 * acc[ai][bj][m][0], d1 = g1 * acc[ai][bj][m][1];
;                         u32x4 w; w.x = cvt_pk_bf16(d0[0], d0[1]); w.y = cvt_pk_bf16(d0[2], d0[3]); w.z = cvt_pk_bf16(d1[0], d1[1]); w.w = cvt_pk_bf16(d1[2], d1[3]);
;                         *(u32x4*)(dbuf + off) = w;
;                         o0 = x0 + (f32x4){__builtin_bit_cast(float, w.x << 16), __builtin_bit_cast(float, w.x & 0xffff0000u), __builtin_bit_cast(float, w.y << 16), __builtin_bit_cast(float, w.y & 0xffff0000u)};
;                         o1 = x1 + (f32x4){__builtin_bit_cast(float, w.z << 16), __builtin_bit_cast(float, w.z & 0xffff0000u), __builtin_bit_cast(float, w.w << 16), __builtin_bit_cast(float, w.w & 0xffff0000u)}; }
;                     else { o0 = x0 + g0 * acc[ai][bj][m][0]; o1 = x1 + g1 * acc[ai][bj][m][1]; *(f32x4*)(out + off) = o0; *(f32x4*)(out + off + 4) = o1; }
;                     if (Hn) { const f32x4 h0 = o0 * G0, h1 = o1 * G1;
;                         u32x4 w; w.x = cvt_pk_bf16(h0[0], h0[1]); w.y = cvt_pk_bf16(h0[2], h0[3]); w.z = cvt_pk_bf16(h1[0], h1[1]); w.w = cvt_pk_bf16(h1[2], h1[3]);
;                         *(u32x4*)(Hn + off) = w;
	v_pk_add_f32 v[126:127], v[160:161], v[126:127]
	s_waitcnt vmcnt(1)
	v_pk_add_f32 v[122:123], v[182:183], v[122:123]
	v_pk_add_f32 v[128:129], v[158:159], v[128:129]
	v_pk_add_f32 v[124:125], v[180:181], v[124:125]
	v_pk_mul_f32 v[160:161], v[198:199], v[126:127]
	v_pk_mul_f32 v[158:159], v[200:201], v[128:129]
	v_pk_mul_f32 v[180:181], v[202:203], v[122:123]
	v_pk_mul_f32 v[182:183], v[204:205], v[124:125]
	v_cvt_pk_bf16_f32 v158, v158, v159
	v_cvt_pk_bf16_f32 v159, v160, v161
	s_nop 0
	v_cvt_pk_bf16_f32 v160, v182, v183
	v_cvt_pk_bf16_f32 v161, v180, v181
	v_lshl_add_u64 v[180:181], s[96:97], 0, v[186:187]
	global_store_dwordx4 v[180:181], v[158:161], off
	s_nop 1
	v_or_b32_e32 v158, 48, v146
	v_ashrrev_i32_e32 v159, 31, v158
	v_lshlrev_b64 v[160:161], 11, v[158:159]
	v_lshl_add_u64 v[190:191], v[160:161], 0, v[148:149]
	v_lshl_add_u64 v[158:159], v[190:191], 2, s[44:45]
	global_load_dwordx4 v[180:183], v[158:159], off nt
	global_load_dwordx4 v[186:189], v[158:159], off offset:16 nt
	v_lshlrev_b64 v[190:191], 1, v[190:191]
	v_cvt_pk_bf16_f32 v118, v118, v119
	v_cvt_pk_bf16_f32 v119, v120, v121
	v_cvt_pk_bf16_f32 v120, v114, v115
	v_cvt_pk_bf16_f32 v121, v116, v117
	v_lshl_add_u64 v[114:115], s[90:91], 0, v[190:191]
	global_store_dwordx4 v[114:115], v[118:121], off
	v_lshlrev_b32_e32 v116, 16, v120
	v_and_b32_e32 v117, 0xffff0000, v120
	v_lshlrev_b32_e32 v114, 16, v121
	v_and_b32_e32 v115, 0xffff0000, v121
	v_lshlrev_b32_e32 v120, 16, v118
	v_and_b32_e32 v121, 0xffff0000, v118
	v_lshlrev_b32_e32 v118, 16, v119
	v_and_b32_e32 v119, 0xffff0000, v119
	s_waitcnt vmcnt(2)
	v_pk_add_f32 v[118:119], v[182:183], v[118:119]
	s_waitcnt vmcnt(1)
	v_pk_add_f32 v[114:115], v[188:189], v[114:115]
	v_pk_add_f32 v[120:121], v[180:181], v[120:121]
	v_pk_add_f32 v[116:117], v[186:187], v[116:117]
	v_pk_mul_f32 v[182:183], v[198:199], v[118:119]
	v_pk_mul_f32 v[180:181], v[200:201], v[120:121]
	v_pk_mul_f32 v[186:187], v[202:203], v[114:115]
	v_pk_mul_f32 v[188:189], v[204:205], v[116:117]
	v_cvt_pk_bf16_f32 v180, v180, v181
	v_cvt_pk_bf16_f32 v181, v182, v183
	s_nop 0
	v_cvt_pk_bf16_f32 v182, v188, v189
	v_cvt_pk_bf16_f32 v183, v186, v187
	v_lshl_add_u64 v[186:187], s[96:97], 0, v[190:191]
	global_store_dwordx4 v[186:187], v[180:183], off
	s_nop 1
	v_lshl_add_u64 v[182:183], v[184:185], 0, s[4:5]
	v_lshl_add_u64 v[194:195], v[182:183], 0, v[148:149]
	v_lshl_add_u64 v[180:181], v[194:195], 2, s[44:45]
	global_load_dwordx4 v[186:189], v[180:181], off nt
	global_load_dwordx4 v[190:193], v[180:181], off offset:16 nt
	v_lshlrev_b64 v[194:195], 1, v[194:195]
	v_cvt_pk_bf16_f32 v110, v110, v111
	v_cvt_pk_bf16_f32 v111, v112, v113
	v_cvt_pk_bf16_f32 v112, v106, v107
	v_cvt_pk_bf16_f32 v113, v108, v109
	v_lshl_add_u64 v[106:107], s[90:91], 0, v[194:195]
	global_store_dwordx4 v[106:107], v[110:113], off
	v_lshlrev_b32_e32 v108, 16, v112
	v_and_b32_e32 v109, 0xffff0000, v112
	v_lshlrev_b32_e32 v106, 16, v113
	v_and_b32_e32 v107, 0xffff0000, v113
	v_lshlrev_b32_e32 v112, 16, v110
	v_and_b32_e32 v113, 0xffff0000, v110
	v_lshlrev_b32_e32 v110, 16, v111
	v_and_b32_e32 v111, 0xffff0000, v111
	s_mov_b64 s[4:5], 0x48000
	s_waitcnt vmcnt(2)
	v_pk_add_f32 v[110:111], v[188:189], v[110:111]
	s_waitcnt vmcnt(1)
	v_pk_add_f32 v[106:107], v[192:193], v[106:107]
	v_pk_add_f32 v[112:113], v[186:187], v[112:113]
	v_pk_add_f32 v[108:109], v[190:191], v[108:109]
	v_pk_mul_f32 v[188:189], v[198:199], v[110:111]
	v_pk_mul_f32 v[186:187], v[200:201], v[112:113]
	v_pk_mul_f32 v[190:191], v[202:203], v[106:107]
	v_pk_mul_f32 v[192:193], v[204:205], v[108:109]
	v_cvt_pk_bf16_f32 v186, v186, v187
	v_cvt_pk_bf16_f32 v187, v188, v189
	s_nop 0
	v_cvt_pk_bf16_f32 v188, v192, v193
	v_cvt_pk_bf16_f32 v189, v190, v191
	v_lshl_add_u64 v[190:191], s[96:97], 0, v[194:195]
	global_store_dwordx4 v[190:191], v[186:189], off
	s_nop 1
	v_lshl_add_u64 v[188:189], v[184:185], 0, s[4:5]
	v_lshl_add_u64 v[212:213], v[188:189], 0, v[148:149]
	v_lshl_add_u64 v[186:187], v[212:213], 2, s[44:45]
	global_load_dwordx4 v[190:193], v[186:187], off nt
	global_load_dwordx4 v[194:197], v[186:187], off offset:16 nt
	v_lshlrev_b64 v[212:213], 1, v[212:213]
	v_cvt_pk_bf16_f32 v94, v94, v95
	v_cvt_pk_bf16_f32 v95, v96, v97
	v_cvt_pk_bf16_f32 v96, v90, v91
	v_cvt_pk_bf16_f32 v97, v92, v93
	v_lshl_add_u64 v[90:91], s[90:91], 0, v[212:213]
	global_store_dwordx4 v[90:91], v[94:97], off
	v_lshlrev_b32_e32 v92, 16, v96
	v_and_b32_e32 v93, 0xffff0000, v96
	v_lshlrev_b32_e32 v90, 16, v97
	v_and_b32_e32 v91, 0xffff0000, v97
	v_lshlrev_b32_e32 v96, 16, v94
	v_and_b32_e32 v97, 0xffff0000, v94
	v_lshlrev_b32_e32 v94, 16, v95
	v_and_b32_e32 v95, 0xffff0000, v95
	s_mov_b64 s[4:5], 0x50000
	s_waitcnt vmcnt(2)
	v_pk_add_f32 v[94:95], v[192:193], v[94:95]
	s_waitcnt vmcnt(1)
	v_pk_add_f32 v[90:91], v[196:197], v[90:91]
	v_pk_add_f32 v[96:97], v[190:191], v[96:97]
	v_pk_add_f32 v[92:93], v[194:195], v[92:93]
	v_pk_mul_f32 v[192:193], v[198:199], v[94:95]
	v_pk_mul_f32 v[190:191], v[200:201], v[96:97]
	v_pk_mul_f32 v[194:195], v[202:203], v[90:91]
	v_pk_mul_f32 v[196:197], v[204:205], v[92:93]
	v_cvt_pk_bf16_f32 v190, v190, v191
	v_cvt_pk_bf16_f32 v191, v192, v193
	s_nop 0
	v_cvt_pk_bf16_f32 v192, v196, v197
	v_cvt_pk_bf16_f32 v193, v194, v195
	v_lshl_add_u64 v[194:195], s[96:97], 0, v[212:213]
	global_store_dwordx4 v[194:195], v[190:193], off
	s_nop 1
	v_lshl_add_u64 v[192:193], v[184:185], 0, s[4:5]
	v_lshl_add_u64 v[220:221], v[192:193], 0, v[148:149]
	v_lshl_add_u64 v[190:191], v[220:221], 2, s[44:45]
	global_load_dwordx4 v[194:197], v[190:191], off nt
	global_load_dwordx4 v[212:215], v[190:191], off offset:16 nt
	v_lshlrev_b64 v[220:221], 1, v[220:221]
	v_cvt_pk_bf16_f32 v86, v86, v87
	v_cvt_pk_bf16_f32 v87, v88, v89
	v_cvt_pk_bf16_f32 v88, v82, v83
	v_cvt_pk_bf16_f32 v89, v84, v85
	v_lshl_add_u64 v[82:83], s[90:91], 0, v[220:221]
	global_store_dwordx4 v[82:83], v[86:89], off
	v_lshlrev_b32_e32 v84, 16, v88
	v_and_b32_e32 v85, 0xffff0000, v88
	v_lshlrev_b32_e32 v82, 16, v89
	v_and_b32_e32 v83, 0xffff0000, v89
	v_lshlrev_b32_e32 v88, 16, v86
	v_and_b32_e32 v89, 0xffff0000, v86
	v_lshlrev_b32_e32 v86, 16, v87
	v_and_b32_e32 v87, 0xffff0000, v87
	s_mov_b64 s[4:5], 0x58000
	s_waitcnt vmcnt(2)
; __device__ __forceinline__ unsigned cvt_pk_bf16(float lo, float hi) { unsigned r; asm volatile("v_cvt_pk_bf16_f32 %0, %1, %2" : "=v"(r) : "v"(lo), "v"(hi)); return r; }
;     __device__ __forceinline__ void operator()(const f32x4 (&acc)[2][2][4][2], const Unit& u, int wr, int wc, int fr, int fq) const {
;     ...
;                 for (int m = 0; m < 4; ++m) { const size_t off = (size_t)(row0 + ai * HALF + m * 16) * 2048 + col0 + bj * HALF;
;                     f32x4 x0 = __builtin_nontemporal_load((const f32x4*)(base + off)), x1 = __builtin_nontemporal_load((const f32x4*)(base + off + 4));
;                     if constexpr (HAS_DIN) { const u32x4 dw = __builtin_nontemporal_load((const u32x4*)(dbuf + off));
;                         x0 += (f32x4){__builtin_bit_cast(float, dw.x << 16), __builtin_bit_cast(float, dw.x & 0xffff0000u), __builtin_bit_cast(float, dw.y << 16), __builtin_bit_cast(float, dw.y & 0xffff0000u)};
;                         x1 += (f32x4){__builtin_bit_cast(float, dw.z << 16), __builtin_bit_cast(float, dw.z & 0xffff0000u), __builtin_bit_cast(float, dw.w << 16), __builtin_bit_cast(float, dw.w & 0xffff0000u)}; }
;                     f32x4 o0, o1;
;                     if constexpr (OUT_DELTA) { const f32x4 d0 = g0 * acc[ai][bj][m][0], d1 = g1 * acc[ai][bj][m][1];
;                         u32x4 w; w.x = cvt_pk_bf16(d0[0], d0[1]); w.y = cvt_pk_bf16(d0[2], d0[3]); w.z = cvt_pk_bf16(d1[0], d1[1]); w.w = cvt_pk_bf16(d1[2], d1[3]);
;                         *(u32x4*)(dbuf + off) = w;
;                         o0 = x0 + (f32x4){__builtin_bit_cast(float, w.x << 16), __builtin_bit_cast(float, w.x & 0xffff0000u), __builtin_bit_cast(float, w.y << 16), __builtin_bit_cast(float, w.y & 0xffff0000u)};
;                         o1 = x1 + (f32x4){__builtin_bit_cast(float, w.z << 16), __builtin_bit_cast(float, w.z & 0xffff0000u), __builtin_bit_cast(float, w.w << 16), __builtin_bit_cast(float, w.w & 0xffff0000u)}; }
;                     else { o0 = x0 + g0 * acc[ai][bj][m][0]; o1 = x1 + g1 * acc[ai][bj][m][1]; *(f32x4*)(out + off) = o0; *(f32x4*)(out + off + 4) = o1; }
;                     if (Hn) { const f32x4 h0 = o0 * G0, h1 = o1 * G1;
;                         u32x4 w; w.x = cvt_pk_bf16(h0[0], h0[1]); w.y = cvt_pk_bf16(h0[2], h0[3]); w.z = cvt_pk_bf16(h1[0], h1[1]); w.w = cvt_pk_bf16(h1[2], h1[3]);
;                         *(u32x4*)(Hn + off) = w;
	v_pk_add_f32 v[86:87], v[196:197], v[86:87]
	s_waitcnt vmcnt(1)
	v_pk_add_f32 v[82:83], v[214:215], v[82:83]
	v_pk_add_f32 v[88:89], v[194:195], v[88:89]
	v_pk_add_f32 v[84:85], v[212:213], v[84:85]
	v_pk_mul_f32 v[196:197], v[198:199], v[86:87]
	v_pk_mul_f32 v[194:195], v[200:201], v[88:89]
	v_pk_mul_f32 v[212:213], v[202:203], v[82:83]
	v_pk_mul_f32 v[214:215], v[204:205], v[84:85]
	v_cvt_pk_bf16_f32 v194, v194, v195
	v_cvt_pk_bf16_f32 v195, v196, v197
	s_nop 0
	v_cvt_pk_bf16_f32 v196, v214, v215
	v_cvt_pk_bf16_f32 v197, v212, v213
	v_lshl_add_u64 v[212:213], s[96:97], 0, v[220:221]
	global_store_dwordx4 v[212:213], v[194:197], off
	s_nop 1
	v_lshl_add_u64 v[196:197], v[184:185], 0, s[4:5]
	v_lshl_add_u64 v[224:225], v[196:197], 0, v[148:149]
	v_lshl_add_u64 v[194:195], v[224:225], 2, s[44:45]
	global_load_dwordx4 v[212:215], v[194:195], off nt
	global_load_dwordx4 v[220:223], v[194:195], off offset:16 nt
	v_lshlrev_b64 v[102:103], 1, v[224:225]
	v_cvt_pk_bf16_f32 v78, v78, v79
	v_cvt_pk_bf16_f32 v79, v80, v81
	v_cvt_pk_bf16_f32 v80, v74, v75
	v_cvt_pk_bf16_f32 v81, v76, v77
	v_lshl_add_u64 v[74:75], s[90:91], 0, v[102:103]
	global_store_dwordx4 v[74:75], v[78:81], off
	v_lshlrev_b32_e32 v76, 16, v80
	v_and_b32_e32 v77, 0xffff0000, v80
	v_lshlrev_b32_e32 v74, 16, v81
	v_and_b32_e32 v75, 0xffff0000, v81
	v_lshlrev_b32_e32 v80, 16, v78
	v_and_b32_e32 v81, 0xffff0000, v78
	v_lshlrev_b32_e32 v78, 16, v79
	v_and_b32_e32 v79, 0xffff0000, v79
	v_lshl_add_u64 v[102:103], s[96:97], 0, v[102:103]
	v_or_b32_e32 v148, 0x80, v148
	s_waitcnt vmcnt(2)
	v_pk_add_f32 v[78:79], v[214:215], v[78:79]
	v_pk_add_f32 v[80:81], v[212:213], v[80:81]
	s_waitcnt vmcnt(1)
	v_pk_add_f32 v[74:75], v[222:223], v[74:75]
	v_pk_add_f32 v[76:77], v[220:221], v[76:77]
	v_pk_mul_f32 v[100:101], v[198:199], v[78:79]
	v_pk_mul_f32 v[98:99], v[200:201], v[80:81]
	v_pk_mul_f32 v[104:105], v[202:203], v[74:75]
	v_pk_mul_f32 v[198:199], v[204:205], v[76:77]
	v_cvt_pk_bf16_f32 v98, v98, v99
	v_cvt_pk_bf16_f32 v99, v100, v101
	s_nop 0
	v_cvt_pk_bf16_f32 v100, v198, v199
	v_cvt_pk_bf16_f32 v101, v104, v105
	global_store_dwordx4 v[102:103], v[98:101], off
	global_load_dwordx4 v[100:103], v[178:179], off offset:512 nt
	global_load_dwordx4 v[198:201], v[178:179], off offset:528 nt
	v_lshl_add_u64 v[98:99], v[184:185], 0, v[148:149]
	v_pk_mul_f32 v[104:105], v[68:69], v[28:29]
	v_pk_mul_f32 v[68:69], v[66:67], v[26:27]
	v_cvt_pk_bf16_f32 v66, v70, v71
	v_cvt_pk_bf16_f32 v67, v72, v73
	s_nop 0
	v_cvt_pk_bf16_f32 v68, v68, v69
	v_cvt_pk_bf16_f32 v69, v104, v105
	v_lshlrev_b64 v[104:105], 1, v[98:99]
	v_lshl_add_u64 v[70:71], s[90:91], 0, v[104:105]
	global_store_dwordx4 v[70:71], v[66:69], off
	v_lshlrev_b32_e32 v72, 16, v68
	v_and_b32_e32 v73, 0xffff0000, v68
	v_lshlrev_b32_e32 v68, 16, v69
	v_and_b32_e32 v69, 0xffff0000, v69
	s_waitcnt vmcnt(1)
	v_pk_add_f32 v[70:71], v[200:201], v[68:69]
	v_lshlrev_b32_e32 v68, 16, v66
	v_and_b32_e32 v69, 0xffff0000, v66
	v_lshlrev_b32_e32 v66, 16, v67
	v_and_b32_e32 v67, 0xffff0000, v67
	v_pk_add_f32 v[98:99], v[102:103], v[66:67]
	v_pk_add_f32 v[100:101], v[100:101], v[68:69]
	v_pk_add_f32 v[72:73], v[198:199], v[72:73]
	v_pk_mul_f32 v[68:69], v[150:151], v[98:99]
	v_pk_mul_f32 v[66:67], v[152:153], v[100:101]
	v_pk_mul_f32 v[102:103], v[154:155], v[70:71]
	v_pk_mul_f32 v[178:179], v[156:157], v[72:73]
	v_cvt_pk_bf16_f32 v66, v66, v67
	v_cvt_pk_bf16_f32 v67, v68, v69
	s_nop 0
	v_cvt_pk_bf16_f32 v68, v178, v179
	v_cvt_pk_bf16_f32 v69, v102, v103
	v_lshl_add_u64 v[102:103], s[96:97], 0, v[104:105]
	global_store_dwordx4 v[102:103], v[66:69], off
	s_nop 1
	v_mul_f32_e32 v66, v101, v101
	v_mul_f32_e32 v67, v99, v99
	v_fmac_f32_e32 v66, v100, v100
	v_fmac_f32_e32 v67, v98, v98
	v_add_f32_e32 v66, v66, v67
	v_mul_f32_e32 v67, v73, v73
	v_mul_f32_e32 v68, v71, v71
	v_fmac_f32_e32 v67, v72, v72
	v_fmac_f32_e32 v68, v70, v70
	v_add_f32_e32 v67, v67, v68
	global_load_dwordx4 v[68:71], v[138:139], off offset:512 nt
	global_load_dwordx4 v[98:101], v[138:139], off offset:528 nt
	v_lshl_add_u64 v[72:73], v[140:141], 0, v[148:149]
	v_lshlrev_b64 v[72:73], 1, v[72:73]
	v_cvt_pk_bf16_f32 v62, v62, v63
	v_cvt_pk_bf16_f32 v63, v64, v65
	v_cvt_pk_bf16_f32 v64, v58, v59
	v_cvt_pk_bf16_f32 v65, v60, v61
	v_lshl_add_u64 v[58:59], s[90:91], 0, v[72:73]
	global_store_dwordx4 v[58:59], v[62:65], off
	v_lshlrev_b32_e32 v60, 16, v64
	v_and_b32_e32 v61, 0xffff0000, v64
	v_lshlrev_b32_e32 v58, 16, v65
	v_and_b32_e32 v59, 0xffff0000, v65
	v_lshlrev_b32_e32 v64, 16, v62
	v_and_b32_e32 v65, 0xffff0000, v62
	v_lshlrev_b32_e32 v62, 16, v63
	v_and_b32_e32 v63, 0xffff0000, v63
	v_lshl_add_u64 v[72:73], s[96:97], 0, v[72:73]
	v_add_f32_e32 v66, v66, v67
	v_add_f32_e32 v66, v211, v66
	s_waitcnt vmcnt(2)
	v_pk_add_f32 v[62:63], v[70:71], v[62:63]
	v_pk_add_f32 v[64:65], v[68:69], v[64:65]
	s_waitcnt vmcnt(1)
	v_pk_add_f32 v[58:59], v[100:101], v[58:59]
	v_pk_add_f32 v[60:61], v[98:99], v[60:61]
	v_pk_mul_f32 v[70:71], v[150:151], v[62:63]
	v_pk_mul_f32 v[68:69], v[152:153], v[64:65]
	v_pk_mul_f32 v[98:99], v[154:155], v[58:59]
	v_pk_mul_f32 v[100:101], v[156:157], v[60:61]
	v_cvt_pk_bf16_f32 v68, v68, v69
	v_cvt_pk_bf16_f32 v69, v70, v71
	s_nop 0
	v_cvt_pk_bf16_f32 v70, v100, v101
	v_cvt_pk_bf16_f32 v71, v98, v99
	global_store_dwordx4 v[72:73], v[68:71], off
	global_load_dwordx4 v[68:71], v[142:143], off offset:512 nt
	s_nop 0
	global_load_dwordx4 v[98:101], v[142:143], off offset:528 nt
	v_lshl_add_u64 v[72:73], v[144:145], 0, v[148:149]
	v_lshlrev_b64 v[72:73], 1, v[72:73]
	v_cvt_pk_bf16_f32 v54, v54, v55
	v_cvt_pk_bf16_f32 v55, v56, v57
	v_cvt_pk_bf16_f32 v56, v50, v51
	v_cvt_pk_bf16_f32 v57, v52, v53
	v_lshl_add_u64 v[50:51], s[90:91], 0, v[72:73]
	global_store_dwordx4 v[50:51], v[54:57], off
	v_lshlrev_b32_e32 v52, 16, v56
	v_and_b32_e32 v53, 0xffff0000, v56
	v_lshlrev_b32_e32 v50, 16, v57
	v_and_b32_e32 v51, 0xffff0000, v57
	v_lshlrev_b32_e32 v56, 16, v54
	v_and_b32_e32 v57, 0xffff0000, v54
	v_lshlrev_b32_e32 v54, 16, v55
	v_and_b32_e32 v55, 0xffff0000, v55
	v_lshl_add_u64 v[72:73], s[96:97], 0, v[72:73]
	s_waitcnt vmcnt(2)
; __device__ __forceinline__ unsigned cvt_pk_bf16(float lo, float hi) { unsigned r; asm volatile("v_cvt_pk_bf16_f32 %0, %1, %2" : "=v"(r) : "v"(lo), "v"(hi)); return r; }
;     __device__ __forceinline__ void operator()(const f32x4 (&acc)[2][2][4][2], const Unit& u, int wr, int wc, int fr, int fq) const {
;     ...
;                 for (int m = 0; m < 4; ++m) { const size_t off = (size_t)(row0 + ai * HALF + m * 16) * 2048 + col0 + bj * HALF;
;                     f32x4 x0 = __builtin_nontemporal_load((const f32x4*)(base + off)), x1 = __builtin_nontemporal_load((const f32x4*)(base + off + 4));
;                     if constexpr (HAS_DIN) { const u32x4 dw = __builtin_nontemporal_load((const u32x4*)(dbuf + off));
;                         x0 += (f32x4){__builtin_bit_cast(float, dw.x << 16), __builtin_bit_cast(float, dw.x & 0xffff0000u), __builtin_bit_cast(float, dw.y << 16), __builtin_bit_cast(float, dw.y & 0xffff0000u)};
;                         x1 += (f32x4){__builtin_bit_cast(float, dw.z << 16), __builtin_bit_cast(float, dw.z & 0xffff0000u), __builtin_bit_cast(float, dw.w << 16), __builtin_bit_cast(float, dw.w & 0xffff0000u)}; }
;                     f32x4 o0, o1;
;                     if constexpr (OUT_DELTA) { const f32x4 d0 = g0 * acc[ai][bj][m][0], d1 = g1 * acc[ai][bj][m][1];
;                         u32x4 w; w.x = cvt_pk_bf16(d0[0], d0[1]); w.y = cvt_pk_bf16(d0[2], d0[3]); w.z = cvt_pk_bf16(d1[0], d1[1]); w.w = cvt_pk_bf16(d1[2], d1[3]);
;                         *(u32x4*)(dbuf + off) = w;
;                         o0 = x0 + (f32x4){__builtin_bit_cast(float, w.x << 16), __builtin_bit_cast(float, w.x & 0xffff0000u), __builtin_bit_cast(float, w.y << 16), __builtin_bit_cast(float, w.y & 0xffff0000u)};
;                         o1 = x1 + (f32x4){__builtin_bit_cast(float, w.z << 16), __builtin_bit_cast(float, w.z & 0xffff0000u), __builtin_bit_cast(float, w.w << 16), __builtin_bit_cast(float, w.w & 0xffff0000u)}; }
;                     else { o0 = x0 + g0 * acc[ai][bj][m][0]; o1 = x1 + g1 * acc[ai][bj][m][1]; *(f32x4*)(out + off) = o0; *(f32x4*)(out + off + 4) = o1; }
;                     if (Hn) { const f32x4 h0 = o0 * G0, h1 = o1 * G1;
;                         u32x4 w; w.x = cvt_pk_bf16(h0[0], h0[1]); w.y = cvt_pk_bf16(h0[2], h0[3]); w.z = cvt_pk_bf16(h1[0], h1[1]); w.w = cvt_pk_bf16(h1[2], h1[3]);
;                         *(u32x4*)(Hn + off) = w;
	v_pk_add_f32 v[54:55], v[70:71], v[54:55]
	v_pk_add_f32 v[56:57], v[68:69], v[56:57]
	s_waitcnt vmcnt(1)
	v_pk_add_f32 v[50:51], v[100:101], v[50:51]
	v_pk_add_f32 v[52:53], v[98:99], v[52:53]
	v_pk_mul_f32 v[70:71], v[150:151], v[54:55]
	v_pk_mul_f32 v[68:69], v[152:153], v[56:57]
	v_pk_mul_f32 v[98:99], v[154:155], v[50:51]
	v_pk_mul_f32 v[100:101], v[156:157], v[52:53]
	v_cvt_pk_bf16_f32 v68, v68, v69
	v_cvt_pk_bf16_f32 v69, v70, v71
	s_nop 0
	v_cvt_pk_bf16_f32 v70, v100, v101
	v_cvt_pk_bf16_f32 v71, v98, v99
	global_store_dwordx4 v[72:73], v[68:71], off
	global_load_dwordx4 v[68:71], v[158:159], off offset:512 nt
	s_nop 0
	global_load_dwordx4 v[98:101], v[158:159], off offset:528 nt
	v_lshl_add_u64 v[72:73], v[160:161], 0, v[148:149]
	v_lshlrev_b64 v[72:73], 1, v[72:73]
	v_cvt_pk_bf16_f32 v46, v46, v47
	v_cvt_pk_bf16_f32 v47, v48, v49
	v_cvt_pk_bf16_f32 v48, v42, v43
	v_cvt_pk_bf16_f32 v49, v44, v45
	v_lshl_add_u64 v[42:43], s[90:91], 0, v[72:73]
	global_store_dwordx4 v[42:43], v[46:49], off
	v_lshlrev_b32_e32 v44, 16, v48
	v_and_b32_e32 v45, 0xffff0000, v48
	v_lshlrev_b32_e32 v42, 16, v49
	v_and_b32_e32 v43, 0xffff0000, v49
	v_lshlrev_b32_e32 v48, 16, v46
	v_and_b32_e32 v49, 0xffff0000, v46
	v_lshlrev_b32_e32 v46, 16, v47
	v_and_b32_e32 v47, 0xffff0000, v47
	v_lshl_add_u64 v[72:73], s[96:97], 0, v[72:73]
	s_waitcnt vmcnt(2)
	v_pk_add_f32 v[46:47], v[70:71], v[46:47]
	v_pk_add_f32 v[48:49], v[68:69], v[48:49]
	s_waitcnt vmcnt(1)
	v_pk_add_f32 v[42:43], v[100:101], v[42:43]
	v_pk_add_f32 v[44:45], v[98:99], v[44:45]
	v_pk_mul_f32 v[70:71], v[150:151], v[46:47]
	v_pk_mul_f32 v[68:69], v[152:153], v[48:49]
	v_pk_mul_f32 v[98:99], v[154:155], v[42:43]
	v_pk_mul_f32 v[100:101], v[156:157], v[44:45]
	v_cvt_pk_bf16_f32 v68, v68, v69
	v_cvt_pk_bf16_f32 v69, v70, v71
	s_nop 0
	v_cvt_pk_bf16_f32 v70, v100, v101
	v_cvt_pk_bf16_f32 v71, v98, v99
	global_store_dwordx4 v[72:73], v[68:71], off
	global_load_dwordx4 v[68:71], v[180:181], off offset:512 nt
	s_nop 0
	global_load_dwordx4 v[98:101], v[180:181], off offset:528 nt
	v_lshl_add_u64 v[72:73], v[182:183], 0, v[148:149]
	v_lshlrev_b64 v[72:73], 1, v[72:73]
	v_cvt_pk_bf16_f32 v38, v38, v39
	v_cvt_pk_bf16_f32 v39, v40, v41
	v_cvt_pk_bf16_f32 v40, v34, v35
	v_cvt_pk_bf16_f32 v41, v36, v37
	v_lshl_add_u64 v[34:35], s[90:91], 0, v[72:73]
	global_store_dwordx4 v[34:35], v[38:41], off
	v_lshlrev_b32_e32 v36, 16, v40
	v_and_b32_e32 v37, 0xffff0000, v40
	v_lshlrev_b32_e32 v34, 16, v41
	v_and_b32_e32 v35, 0xffff0000, v41
	v_lshlrev_b32_e32 v40, 16, v38
	v_and_b32_e32 v41, 0xffff0000, v38
	v_lshlrev_b32_e32 v38, 16, v39
	v_and_b32_e32 v39, 0xffff0000, v39
	v_lshl_add_u64 v[72:73], s[96:97], 0, v[72:73]
	s_waitcnt vmcnt(2)
	v_pk_add_f32 v[38:39], v[70:71], v[38:39]
	v_pk_add_f32 v[40:41], v[68:69], v[40:41]
	s_waitcnt vmcnt(1)
	v_pk_add_f32 v[34:35], v[100:101], v[34:35]
	v_pk_add_f32 v[36:37], v[98:99], v[36:37]
	v_pk_mul_f32 v[70:71], v[150:151], v[38:39]
	v_pk_mul_f32 v[68:69], v[152:153], v[40:41]
	v_pk_mul_f32 v[98:99], v[154:155], v[34:35]
	v_pk_mul_f32 v[100:101], v[156:157], v[36:37]
	v_cvt_pk_bf16_f32 v68, v68, v69
	v_cvt_pk_bf16_f32 v69, v70, v71
	s_nop 0
	v_cvt_pk_bf16_f32 v70, v100, v101
	v_cvt_pk_bf16_f32 v71, v98, v99
	global_store_dwordx4 v[72:73], v[68:71], off
	global_load_dwordx4 v[68:71], v[186:187], off offset:512 nt
	s_nop 0
	global_load_dwordx4 v[98:101], v[186:187], off offset:528 nt
	v_lshl_add_u64 v[72:73], v[188:189], 0, v[148:149]
	v_lshlrev_b64 v[72:73], 1, v[72:73]
	v_cvt_pk_bf16_f32 v22, v22, v23
	v_cvt_pk_bf16_f32 v23, v24, v25
	v_cvt_pk_bf16_f32 v24, v18, v19
	v_cvt_pk_bf16_f32 v25, v20, v21
	v_lshl_add_u64 v[18:19], s[90:91], 0, v[72:73]
	global_store_dwordx4 v[18:19], v[22:25], off
	v_lshlrev_b32_e32 v20, 16, v24
	v_and_b32_e32 v21, 0xffff0000, v24
	v_lshlrev_b32_e32 v18, 16, v25
	v_and_b32_e32 v19, 0xffff0000, v25
	v_lshlrev_b32_e32 v24, 16, v22
	v_and_b32_e32 v25, 0xffff0000, v22
	v_lshlrev_b32_e32 v22, 16, v23
	v_and_b32_e32 v23, 0xffff0000, v23
	v_lshl_add_u64 v[72:73], s[96:97], 0, v[72:73]
	s_waitcnt vmcnt(2)
	v_pk_add_f32 v[22:23], v[70:71], v[22:23]
	v_pk_add_f32 v[24:25], v[68:69], v[24:25]
	s_waitcnt vmcnt(1)
; __device__ __forceinline__ unsigned cvt_pk_bf16(float lo, float hi) { unsigned r; asm volatile("v_cvt_pk_bf16_f32 %0, %1, %2" : "=v"(r) : "v"(lo), "v"(hi)); return r; }
;     __device__ __forceinline__ void operator()(const f32x4 (&acc)[2][2][4][2], const Unit& u, int wr, int wc, int fr, int fq) const {
;     ...
;                 for (int m = 0; m < 4; ++m) { const size_t off = (size_t)(row0 + ai * HALF + m * 16) * 2048 + col0 + bj * HALF;
;                     f32x4 x0 = __builtin_nontemporal_load((const f32x4*)(base + off)), x1 = __builtin_nontemporal_load((const f32x4*)(base + off + 4));
;                     if constexpr (HAS_DIN) { const u32x4 dw = __builtin_nontemporal_load((const u32x4*)(dbuf + off));
;                         x0 += (f32x4){__builtin_bit_cast(float, dw.x << 16), __builtin_bit_cast(float, dw.x & 0xffff0000u), __builtin_bit_cast(float, dw.y << 16), __builtin_bit_cast(float, dw.y & 0xffff0000u)};
;                         x1 += (f32x4){__builtin_bit_cast(float, dw.z << 16), __builtin_bit_cast(float, dw.z & 0xffff0000u), __builtin_bit_cast(float, dw.w << 16), __builtin_bit_cast(float, dw.w & 0xffff0000u)}; }
;                     f32x4 o0, o1;
;                     if constexpr (OUT_DELTA) { const f32x4 d0 = g0 * acc[ai][bj][m][0], d1 = g1 * acc[ai][bj][m][1];
;                         u32x4 w; w.x = cvt_pk_bf16(d0[0], d0[1]); w.y = cvt_pk_bf16(d0[2], d0[3]); w.z = cvt_pk_bf16(d1[0], d1[1]); w.w = cvt_pk_bf16(d1[2], d1[3]);
;                         *(u32x4*)(dbuf + off) = w;
;                         o0 = x0 + (f32x4){__builtin_bit_cast(float, w.x << 16), __builtin_bit_cast(float, w.x & 0xffff0000u), __builtin_bit_cast(float, w.y << 16), __builtin_bit_cast(float, w.y & 0xffff0000u)};
;                         o1 = x1 + (f32x4){__builtin_bit_cast(float, w.z << 16), __builtin_bit_cast(float, w.z & 0xffff0000u), __builtin_bit_cast(float, w.w << 16), __builtin_bit_cast(float, w.w & 0xffff0000u)}; }
;                     else { o0 = x0 + g0 * acc[ai][bj][m][0]; o1 = x1 + g1 * acc[ai][bj][m][1]; *(f32x4*)(out + off) = o0; *(f32x4*)(out + off + 4) = o1; }
;                     if (Hn) { const f32x4 h0 = o0 * G0, h1 = o1 * G1;
;                         u32x4 w; w.x = cvt_pk_bf16(h0[0], h0[1]); w.y = cvt_pk_bf16(h0[2], h0[3]); w.z = cvt_pk_bf16(h1[0], h1[1]); w.w = cvt_pk_bf16(h1[2], h1[3]);
;                         *(u32x4*)(Hn + off) = w;
	v_pk_add_f32 v[18:19], v[100:101], v[18:19]
	v_pk_add_f32 v[20:21], v[98:99], v[20:21]
	v_pk_mul_f32 v[70:71], v[150:151], v[22:23]
	v_pk_mul_f32 v[68:69], v[152:153], v[24:25]
	v_pk_mul_f32 v[98:99], v[154:155], v[18:19]
	v_pk_mul_f32 v[100:101], v[156:157], v[20:21]
	v_cvt_pk_bf16_f32 v68, v68, v69
	v_cvt_pk_bf16_f32 v69, v70, v71
	s_nop 0
	v_cvt_pk_bf16_f32 v70, v100, v101
	v_cvt_pk_bf16_f32 v71, v98, v99
	global_store_dwordx4 v[72:73], v[68:71], off
	global_load_dwordx4 v[68:71], v[190:191], off offset:512 nt
	s_nop 0
	global_load_dwordx4 v[98:101], v[190:191], off offset:528 nt
	v_lshl_add_u64 v[72:73], v[192:193], 0, v[148:149]
	v_lshlrev_b64 v[72:73], 1, v[72:73]
	v_cvt_pk_bf16_f32 v14, v14, v15
	v_cvt_pk_bf16_f32 v15, v16, v17
	v_cvt_pk_bf16_f32 v16, v10, v11
	v_cvt_pk_bf16_f32 v17, v12, v13
	v_lshl_add_u64 v[10:11], s[90:91], 0, v[72:73]
	global_store_dwordx4 v[10:11], v[14:17], off
	v_lshlrev_b32_e32 v12, 16, v16
	v_and_b32_e32 v13, 0xffff0000, v16
	v_lshlrev_b32_e32 v10, 16, v17
	v_and_b32_e32 v11, 0xffff0000, v17
	v_lshlrev_b32_e32 v16, 16, v14
	v_and_b32_e32 v17, 0xffff0000, v14
	v_lshlrev_b32_e32 v14, 16, v15
	v_and_b32_e32 v15, 0xffff0000, v15
	v_lshl_add_u64 v[72:73], s[96:97], 0, v[72:73]
	s_waitcnt vmcnt(2)
	v_pk_add_f32 v[14:15], v[70:71], v[14:15]
	v_pk_add_f32 v[16:17], v[68:69], v[16:17]
	s_waitcnt vmcnt(1)
	v_pk_add_f32 v[10:11], v[100:101], v[10:11]
	v_pk_add_f32 v[12:13], v[98:99], v[12:13]
	v_pk_mul_f32 v[70:71], v[150:151], v[14:15]
	v_pk_mul_f32 v[68:69], v[152:153], v[16:17]
	v_pk_mul_f32 v[98:99], v[154:155], v[10:11]
	v_pk_mul_f32 v[100:101], v[156:157], v[12:13]
	v_cvt_pk_bf16_f32 v68, v68, v69
	v_cvt_pk_bf16_f32 v69, v70, v71
	s_nop 0
	v_cvt_pk_bf16_f32 v70, v100, v101
	v_cvt_pk_bf16_f32 v71, v98, v99
	global_store_dwordx4 v[72:73], v[68:71], off
	global_load_dwordx4 v[68:71], v[194:195], off offset:512 nt
	s_nop 0
	global_load_dwordx4 v[98:101], v[194:195], off offset:528 nt
	v_lshl_add_u64 v[72:73], v[196:197], 0, v[148:149]
	v_lshlrev_b64 v[30:31], 1, v[72:73]
	v_cvt_pk_bf16_f32 v6, v6, v7
	v_cvt_pk_bf16_f32 v7, v8, v9
	v_cvt_pk_bf16_f32 v8, v2, v3
	v_cvt_pk_bf16_f32 v9, v4, v5
	v_lshl_add_u64 v[2:3], s[90:91], 0, v[30:31]
	global_store_dwordx4 v[2:3], v[6:9], off
	v_lshlrev_b32_e32 v4, 16, v8
	v_and_b32_e32 v5, 0xffff0000, v8
	v_lshlrev_b32_e32 v2, 16, v9
	v_and_b32_e32 v3, 0xffff0000, v9
	v_lshlrev_b32_e32 v8, 16, v6
	v_and_b32_e32 v9, 0xffff0000, v6
	v_lshlrev_b32_e32 v6, 16, v7
	v_and_b32_e32 v7, 0xffff0000, v7
	v_lshl_add_u64 v[30:31], s[96:97], 0, v[30:31]
	s_waitcnt vmcnt(2)
	v_pk_add_f32 v[8:9], v[68:69], v[8:9]
	v_pk_add_f32 v[6:7], v[70:71], v[6:7]
	v_pk_mul_f32 v[26:27], v[152:153], v[8:9]
	s_waitcnt vmcnt(1)
	v_pk_add_f32 v[2:3], v[100:101], v[2:3]
	v_pk_add_f32 v[4:5], v[98:99], v[4:5]
	v_pk_mul_f32 v[28:29], v[150:151], v[6:7]
	v_cvt_pk_bf16_f32 v26, v26, v27
	v_pk_mul_f32 v[32:33], v[154:155], v[2:3]
	v_cvt_pk_bf16_f32 v27, v28, v29
	v_pk_mul_f32 v[68:69], v[156:157], v[4:5]
	s_nop 0
	v_cvt_pk_bf16_f32 v28, v68, v69
	v_cvt_pk_bf16_f32 v29, v32, v33
	global_store_dwordx4 v[30:31], v[26:29], off
	s_nop 1
	v_and_b32_e32 v27, 64, v218
	v_xor_b32_e32 v26, 16, v218
	v_add_u32_e32 v27, 64, v27
	v_cmp_lt_i32_e32 vcc, v26, v27
	s_nop 1
	v_cndmask_b32_e32 v26, v218, v26, vcc
	v_lshlrev_b32_e32 v28, 2, v26
	v_xor_b32_e32 v26, 32, v218
	v_cmp_lt_i32_e32 vcc, v26, v27
	s_nop 1
	v_cndmask_b32_e32 v26, v218, v26, vcc
	v_lshlrev_b32_e32 v29, 2, v26
	ds_bpermute_b32 v26, v28, v66
	s_waitcnt lgkmcnt(0)
	v_add_f32_e32 v30, v66, v26
	ds_bpermute_b32 v31, v29, v30
	v_lshl_add_u64 v[26:27], v[146:147], 3, s[42:43]
	s_and_saveexec_b64 s[4:5], s[0:1]
	s_mov_b32 s8, 0x2f800000
	s_mov_b32 s9, 0xcf800000
	s_cbranch_execz .LBB0_558
	s_waitcnt lgkmcnt(0)
	v_add_f32_e32 v30, v30, v31
	v_mul_f32_e32 v30, 0x47800000, v30
	v_rndne_f32_e32 v30, v30
	v_mul_f32_e64 v31, |v30|, s8
	v_floor_f32_e32 v31, v31
	v_fma_f32 v32, v31, s9, |v30|
	v_cvt_u32_f32_e32 v32, v32
	v_cvt_u32_f32_e32 v31, v31
	v_ashrrev_i32_e32 v33, 31, v30
	v_xor_b32_e32 v30, v32, v33
	v_xor_b32_e32 v31, v31, v33
	v_sub_co_u32_e32 v30, vcc, v30, v33
	s_nop 1
	v_subb_co_u32_e32 v31, vcc, v31, v33, vcc
	global_atomic_add_x2 v[26:27], v[30:31], off

; #define PG8_STAGE(bufoff, gbase, voff) do { const char* gb_ = (const char*)(gbase); asm volatile("" : "+s"(gb_)); _Pragma("unroll") for (int _i = 0; _i < 2; ++_i) { unsigned vo_ = (voff)[_i]; asm volatile("" : "+v"(vo_));        \
;         __builtin_amdgcn_global_load_lds((const unsigned*)(gb_ + vo_), (PG8_LAS unsigned*)(lds + (bufoff) + ldsw + _i * 8192), 16, 0, 0); } } while (0)
; #define PG8_LDA(dst, b, h) do { _Pragma("unroll") for (int m = 0; m < 4; ++m) _Pragma("unroll") for (int k = 0; k < 2; ++k) dst[m][k] = *(const PG8_LAS bf16x8*)(lds + PG8_SA(b, h) + aoff + m * 2048 + k * 1024); } while (0)
; #define PG8_LDB(dst, b, h) do { _Pragma("unroll") for (int n = 0; n < 2; ++n) _Pragma("unroll") for (int k = 0; k < 2; ++k) dst[n][k] = *(const PG8_LAS bf16x8*)(lds + PG8_SB(b, h) + boff + n * 2048 + k * 1024); } while (0)
; #define PG8_MMA(ai, bj, At, Bt) do { __builtin_amdgcn_s_setprio(1); _Pragma("unroll") for (int m = 0; m < 4; ++m) _Pragma("unroll") for (int n = 0; n < 2; ++n) _Pragma("unroll") for (int k = 0; k < 2; ++k) \
;         acc[ai][bj][m][n] = __builtin_amdgcn_mfma_f32_16x16x32_bf16(Bt[n][k], At[m][k], acc[ai][bj][m][n], 0, 0, 0); __builtin_amdgcn_s_setprio(0); } while (0)
; #define PG8_WAIT_V(n) asm volatile("s_waitcnt vmcnt(" #n ")" ::: "memory")
; #define PG8_WAIT_L(n) asm volatile("s_waitcnt lgkmcnt(" #n ")" ::: "memory")
; #define PG8_BAR __builtin_amdgcn_s_barrier()
; #define PG8_SCHED __builtin_amdgcn_sched_barrier(0)
; template <class Epi, class Sched, bool ALIGN_EPI = false, bool SP2 = false>
; __device__ __forceinline__ void gemm_phase(PG8_LAS unsigned char* lds, const Gemm g, const Sched& S, const Epi& E) {
;     ...
;             PG8_LDB(B0, 0, 0); PG8_LDB(B1, 0, 1); PG8_SCHED; PG8_LDA(At, 0, 0); PG8_STAGE(PG8_SA(1, 1), a1 + hstep, voffA);
;             PG8_WAIT_V(8); PG8_WAIT_L(0); PG8_BAR; PG8_MMA(0, 0, At, B0); PG8_MMA(0, 1, At, B1); PG8_BAR; PG8_SCHED;
;             PG8_LDA(At, 0, 1); PG8_STAGE(PG8_SB(0, 0), b2, voffB); PG8_STAGE(PG8_SB(0, 1), b2 + hstep, voffB); PG8_STAGE(PG8_SA(0, 0), a2, voffA);
.LBB0_707:
	s_add_u32 s2, s4, 0x100
	s_addc_u32 s3, s5, 0
	s_cmpk_eq_i32 s35, 0x54
	s_cselect_b32 s10, s52, s2
	s_cselect_b32 s11, s53, s3
	s_cselect_b32 s8, s42, s31
	s_cselect_b32 s9, s43, s34
	s_add_u32 s6, s10, 0x80
	s_addc_u32 s7, s11, 0
	s_add_i32 s38, 0, 0x10000
	s_add_i32 s39, 0, 0x14000
	v_add_u32_e32 v102, s38, v192
	v_add_u32_e32 v158, s39, v192
	ds_read_b128 v[34:37], v102
	ds_read_b128 v[38:41], v102 offset:1024
	ds_read_b128 v[98:101], v102 offset:2048
	ds_read_b128 v[102:105], v102 offset:3072
	ds_read_b128 v[146:149], v158
	ds_read_b128 v[150:153], v158 offset:1024
	ds_read_b128 v[154:157], v158 offset:2048
	ds_read_b128 v[158:161], v158 offset:3072
	s_add_u32 s4, s4, 0x160080
	s_addc_u32 s5, s5, 0
	v_mov_b32_e32 v195, v1
	ds_read_b128 v[178:181], v194
	ds_read_b128 v[182:185], v194 offset:1024
	ds_read_b128 v[186:189], v194 offset:2048
	ds_read_b128 v[196:199], v194 offset:3072
	ds_read_b128 v[200:203], v194 offset:4096
	ds_read_b128 v[204:207], v194 offset:5120
	ds_read_b128 v[208:211], v194 offset:6144
	ds_read_b128 v[212:215], v194 offset:7168
	s_add_i32 m0, s16, 0xc000
	s_nop 0
	global_load_lds_dwordx4 v195, s[4:5]
	v_mov_b32_e32 v195, v164
	s_add_i32 m0, s16, 0xe000
	s_nop 0
	global_load_lds_dwordx4 v195, s[4:5]
	s_waitcnt vmcnt(8)
	s_waitcnt lgkmcnt(0)
	s_barrier
	s_setprio 1
	s_waitcnt lgkmcnt(0)
	v_mfma_f32_16x16x32_bf16 v[142:145], v[34:37], v[178:181], v[142:145]
	v_mfma_f32_16x16x32_bf16 v[142:145], v[38:41], v[182:185], v[142:145]
	v_mfma_f32_16x16x32_bf16 v[134:137], v[34:37], v[186:189], v[134:137]
	v_mfma_f32_16x16x32_bf16 v[134:137], v[38:41], v[196:199], v[134:137]
	v_mfma_f32_16x16x32_bf16 v[126:129], v[34:37], v[200:203], v[126:129]
	v_mfma_f32_16x16x32_bf16 v[126:129], v[38:41], v[204:207], v[126:129]
	v_mfma_f32_16x16x32_bf16 v[118:121], v[34:37], v[208:211], v[118:121]
	v_mfma_f32_16x16x32_bf16 v[118:121], v[38:41], v[212:215], v[118:121]
	v_mfma_f32_16x16x32_bf16 v[138:141], v[98:101], v[178:181], v[138:141]
	v_mfma_f32_16x16x32_bf16 v[138:141], v[102:105], v[182:185], v[138:141]
	v_mfma_f32_16x16x32_bf16 v[130:133], v[98:101], v[186:189], v[130:133]
	v_mfma_f32_16x16x32_bf16 v[130:133], v[102:105], v[196:199], v[130:133]
	v_mfma_f32_16x16x32_bf16 v[122:125], v[98:101], v[200:203], v[122:125]
	v_mfma_f32_16x16x32_bf16 v[122:125], v[102:105], v[204:207], v[122:125]
	v_mfma_f32_16x16x32_bf16 v[114:117], v[98:101], v[208:211], v[114:117]
	v_mfma_f32_16x16x32_bf16 v[114:117], v[102:105], v[212:215], v[114:117]
	s_setprio 0
	s_setprio 1
	v_mfma_f32_16x16x32_bf16 v[70:73], v[146:149], v[178:181], v[70:73]
	v_mfma_f32_16x16x32_bf16 v[70:73], v[150:153], v[182:185], v[70:73]
	v_mfma_f32_16x16x32_bf16 v[62:65], v[146:149], v[186:189], v[62:65]
	v_mfma_f32_16x16x32_bf16 v[62:65], v[150:153], v[196:199], v[62:65]
	v_mfma_f32_16x16x32_bf16 v[54:57], v[146:149], v[200:203], v[54:57]
	v_mfma_f32_16x16x32_bf16 v[54:57], v[150:153], v[204:207], v[54:57]
	v_mfma_f32_16x16x32_bf16 v[46:49], v[146:149], v[208:211], v[46:49]
	v_mfma_f32_16x16x32_bf16 v[46:49], v[150:153], v[212:215], v[46:49]
	v_mfma_f32_16x16x32_bf16 v[66:69], v[154:157], v[178:181], v[66:69]
	v_mfma_f32_16x16x32_bf16 v[66:69], v[158:161], v[182:185], v[66:69]
	v_mfma_f32_16x16x32_bf16 v[58:61], v[154:157], v[186:189], v[58:61]
	v_mfma_f32_16x16x32_bf16 v[58:61], v[158:161], v[196:199], v[58:61]
	v_mfma_f32_16x16x32_bf16 v[50:53], v[154:157], v[200:203], v[50:53]
	v_mfma_f32_16x16x32_bf16 v[50:53], v[158:161], v[204:207], v[50:53]
	v_mfma_f32_16x16x32_bf16 v[42:45], v[154:157], v[208:211], v[42:45]
	v_mfma_f32_16x16x32_bf16 v[42:45], v[158:161], v[212:215], v[42:45]
	s_setprio 0
	s_barrier
	s_mov_b64 s[4:5], s[8:9]
	v_mov_b32_e32 v195, v162
	s_add_i32 s38, s38, s15
	ds_read_b128 v[178:181], v194 offset:16384
	ds_read_b128 v[182:185], v194 offset:17408
	ds_read_b128 v[186:189], v194 offset:18432
	ds_read_b128 v[196:199], v194 offset:19456
	ds_read_b128 v[200:203], v194 offset:20480
	ds_read_b128 v[204:207], v194 offset:21504
	ds_read_b128 v[208:211], v194 offset:22528
	ds_read_b128 v[212:215], v194 offset:23552
	s_mov_b32 m0, s38
	s_nop 0
	global_load_lds_dwordx4 v195, s[4:5]
	v_mov_b32_e32 v195, v190
	s_add_i32 m0, s38, 0x2000
	s_nop 0
	global_load_lds_dwordx4 v195, s[4:5]
	s_add_u32 s4, s8, 0x160000
	s_addc_u32 s5, s9, 0
	v_mov_b32_e32 v195, v162
	s_add_i32 s38, s39, s15
	s_mov_b32 m0, s38
	s_nop 0
	global_load_lds_dwordx4 v195, s[4:5]
	v_mov_b32_e32 v195, v190
	s_add_i32 m0, s38, 0x2000
	s_nop 0
	global_load_lds_dwordx4 v195, s[4:5]
	s_mov_b64 s[4:5], s[10:11]
	v_mov_b32_e32 v195, v1
	s_mov_b32 m0, s16
	s_nop 0
	global_load_lds_dwordx4 v195, s[4:5]
	v_mov_b32_e32 v195, v164
	s_mov_b32 m0, s17
	s_nop 0
	global_load_lds_dwordx4 v195, s[4:5]
	s_waitcnt vmcnt(8)
	s_waitcnt lgkmcnt(0)
	s_barrier
; #define PG8_STAGE(bufoff, gbase, voff) do { const char* gb_ = (const char*)(gbase); asm volatile("" : "+s"(gb_)); _Pragma("unroll") for (int _i = 0; _i < 2; ++_i) { unsigned vo_ = (voff)[_i]; asm volatile("" : "+v"(vo_));        \
;         __builtin_amdgcn_global_load_lds((const unsigned*)(gb_ + vo_), (PG8_LAS unsigned*)(lds + (bufoff) + ldsw + _i * 8192), 16, 0, 0); } } while (0)
; #define PG8_LDA(dst, b, h) do { _Pragma("unroll") for (int m = 0; m < 4; ++m) _Pragma("unroll") for (int k = 0; k < 2; ++k) dst[m][k] = *(const PG8_LAS bf16x8*)(lds + PG8_SA(b, h) + aoff + m * 2048 + k * 1024); } while (0)
; #define PG8_LDB(dst, b, h) do { _Pragma("unroll") for (int n = 0; n < 2; ++n) _Pragma("unroll") for (int k = 0; k < 2; ++k) dst[n][k] = *(const PG8_LAS bf16x8*)(lds + PG8_SB(b, h) + boff + n * 2048 + k * 1024); } while (0)
; #define PG8_MMA(ai, bj, At, Bt) do { __builtin_amdgcn_s_setprio(1); _Pragma("unroll") for (int m = 0; m < 4; ++m) _Pragma("unroll") for (int n = 0; n < 2; ++n) _Pragma("unroll") for (int k = 0; k < 2; ++k) \
;         acc[ai][bj][m][n] = __builtin_amdgcn_mfma_f32_16x16x32_bf16(Bt[n][k], At[m][k], acc[ai][bj][m][n], 0, 0, 0); __builtin_amdgcn_s_setprio(0); } while (0)
; #define PG8_WAIT_V(n) asm volatile("s_waitcnt vmcnt(" #n ")" ::: "memory")
; #define PG8_WAIT_L(n) asm volatile("s_waitcnt lgkmcnt(" #n ")" ::: "memory")
; #define PG8_BAR __builtin_amdgcn_s_barrier()
; #define PG8_SCHED __builtin_amdgcn_sched_barrier(0)
; template <class Epi, class Sched, bool ALIGN_EPI = false, bool SP2 = false>
; __device__ __forceinline__ void gemm_phase(PG8_LAS unsigned char* lds, const Gemm g, const Sched& S, const Epi& E) {
;     ...
;             PG8_WAIT_V(8); PG8_WAIT_L(0); PG8_BAR; PG8_MMA(1, 0, At, B0); PG8_MMA(1, 1, At, B1); PG8_BAR; PG8_SCHED;
;             PG8_LDB(B0, 1, 0); PG8_LDB(B1, 1, 1); PG8_SCHED; PG8_LDA(At, 1, 0); PG8_STAGE(PG8_SA(0, 1), a2 + hstep, voffA);
;             PG8_WAIT_V(8); PG8_WAIT_L(0); PG8_BAR; PG8_MMA(0, 0, At, B0); PG8_MMA(0, 1, At, B1); PG8_BAR; PG8_SCHED;
	s_setprio 1
	s_waitcnt lgkmcnt(0)
	v_mfma_f32_16x16x32_bf16 v[110:113], v[34:37], v[178:181], v[110:113]
	v_mfma_f32_16x16x32_bf16 v[110:113], v[38:41], v[182:185], v[110:113]
	v_mfma_f32_16x16x32_bf16 v[94:97], v[34:37], v[186:189], v[94:97]
	v_mfma_f32_16x16x32_bf16 v[94:97], v[38:41], v[196:199], v[94:97]
	v_mfma_f32_16x16x32_bf16 v[86:89], v[34:37], v[200:203], v[86:89]
	v_mfma_f32_16x16x32_bf16 v[86:89], v[38:41], v[204:207], v[86:89]
	v_mfma_f32_16x16x32_bf16 v[34:37], v[34:37], v[208:211], v[78:81]
	v_mfma_f32_16x16x32_bf16 v[34:37], v[38:41], v[212:215], v[34:37]
	v_mfma_f32_16x16x32_bf16 v[106:109], v[98:101], v[178:181], v[106:109]
	v_mfma_f32_16x16x32_bf16 v[106:109], v[102:105], v[182:185], v[106:109]
	v_mfma_f32_16x16x32_bf16 v[90:93], v[98:101], v[186:189], v[90:93]
	v_mfma_f32_16x16x32_bf16 v[90:93], v[102:105], v[196:199], v[90:93]
	v_mfma_f32_16x16x32_bf16 v[82:85], v[98:101], v[200:203], v[82:85]
	v_mfma_f32_16x16x32_bf16 v[82:85], v[102:105], v[204:207], v[82:85]
	v_mfma_f32_16x16x32_bf16 v[38:41], v[98:101], v[208:211], v[74:77]
	v_mfma_f32_16x16x32_bf16 v[38:41], v[102:105], v[212:215], v[38:41]
	s_setprio 0
	s_setprio 1
	v_mfma_f32_16x16x32_bf16 v[30:33], v[146:149], v[178:181], v[30:33]
	v_mfma_f32_16x16x32_bf16 v[30:33], v[150:153], v[182:185], v[30:33]
	v_mfma_f32_16x16x32_bf16 v[22:25], v[146:149], v[186:189], v[22:25]
	v_mfma_f32_16x16x32_bf16 v[22:25], v[150:153], v[196:199], v[22:25]
	v_mfma_f32_16x16x32_bf16 v[14:17], v[146:149], v[200:203], v[14:17]
	v_mfma_f32_16x16x32_bf16 v[14:17], v[150:153], v[204:207], v[14:17]
	v_mfma_f32_16x16x32_bf16 v[6:9], v[146:149], v[208:211], v[6:9]
	v_mfma_f32_16x16x32_bf16 v[6:9], v[150:153], v[212:215], v[6:9]
	v_mfma_f32_16x16x32_bf16 v[26:29], v[154:157], v[178:181], v[26:29]
	v_mfma_f32_16x16x32_bf16 v[26:29], v[158:161], v[182:185], v[26:29]
	v_mfma_f32_16x16x32_bf16 v[18:21], v[154:157], v[186:189], v[18:21]
	v_mfma_f32_16x16x32_bf16 v[18:21], v[158:161], v[196:199], v[18:21]
	v_mfma_f32_16x16x32_bf16 v[10:13], v[154:157], v[200:203], v[10:13]
	v_mfma_f32_16x16x32_bf16 v[10:13], v[158:161], v[204:207], v[10:13]
	v_mfma_f32_16x16x32_bf16 v[2:5], v[154:157], v[208:211], v[2:5]
	v_mfma_f32_16x16x32_bf16 v[2:5], v[158:161], v[212:215], v[2:5]
	s_setprio 0
	s_barrier
	s_add_i32 s38, 0, 0x18000
	s_add_i32 s39, 0, 0x1c000
	v_add_u32_e32 v102, s38, v192
	v_add_u32_e32 v158, s39, v192
	ds_read_b128 v[74:77], v102
	ds_read_b128 v[78:81], v102 offset:1024
	ds_read_b128 v[98:101], v102 offset:2048
	ds_read_b128 v[102:105], v102 offset:3072
	ds_read_b128 v[146:149], v158
	ds_read_b128 v[150:153], v158 offset:1024
	ds_read_b128 v[154:157], v158 offset:2048
	ds_read_b128 v[158:161], v158 offset:3072
	s_add_u32 s4, s10, 0x160000
	s_addc_u32 s5, s11, 0
	v_mov_b32_e32 v195, v1
	s_mov_b32 m0, s18
	ds_read_b128 v[178:181], v194 offset:32768
	ds_read_b128 v[182:185], v194 offset:33792
	ds_read_b128 v[186:189], v194 offset:34816
	ds_read_b128 v[196:199], v194 offset:35840
	ds_read_b128 v[200:203], v194 offset:36864
	ds_read_b128 v[204:207], v194 offset:37888
	ds_read_b128 v[208:211], v194 offset:38912
	ds_read_b128 v[212:215], v194 offset:39936
	s_nop 0
	global_load_lds_dwordx4 v195, s[4:5]
	v_mov_b32_e32 v195, v164
	s_mov_b32 m0, s19
	s_nop 0
	global_load_lds_dwordx4 v195, s[4:5]
	s_waitcnt vmcnt(8)
	s_waitcnt lgkmcnt(0)
	s_barrier
	s_setprio 1
	s_waitcnt lgkmcnt(0)
	v_mfma_f32_16x16x32_bf16 v[142:145], v[74:77], v[178:181], v[142:145]
	v_mfma_f32_16x16x32_bf16 v[142:145], v[78:81], v[182:185], v[142:145]
	v_mfma_f32_16x16x32_bf16 v[134:137], v[74:77], v[186:189], v[134:137]
	v_mfma_f32_16x16x32_bf16 v[134:137], v[78:81], v[196:199], v[134:137]
	v_mfma_f32_16x16x32_bf16 v[126:129], v[74:77], v[200:203], v[126:129]
	v_mfma_f32_16x16x32_bf16 v[126:129], v[78:81], v[204:207], v[126:129]
	v_mfma_f32_16x16x32_bf16 v[118:121], v[74:77], v[208:211], v[118:121]
	v_mfma_f32_16x16x32_bf16 v[118:121], v[78:81], v[212:215], v[118:121]
	v_mfma_f32_16x16x32_bf16 v[138:141], v[98:101], v[178:181], v[138:141]
	v_mfma_f32_16x16x32_bf16 v[138:141], v[102:105], v[182:185], v[138:141]
	v_mfma_f32_16x16x32_bf16 v[130:133], v[98:101], v[186:189], v[130:133]
	v_mfma_f32_16x16x32_bf16 v[130:133], v[102:105], v[196:199], v[130:133]
	v_mfma_f32_16x16x32_bf16 v[122:125], v[98:101], v[200:203], v[122:125]
	v_mfma_f32_16x16x32_bf16 v[122:125], v[102:105], v[204:207], v[122:125]
	v_mfma_f32_16x16x32_bf16 v[114:117], v[98:101], v[208:211], v[114:117]
	v_mfma_f32_16x16x32_bf16 v[114:117], v[102:105], v[212:215], v[114:117]
	s_setprio 0
	s_setprio 1
	v_mfma_f32_16x16x32_bf16 v[70:73], v[146:149], v[178:181], v[70:73]
	v_mfma_f32_16x16x32_bf16 v[70:73], v[150:153], v[182:185], v[70:73]
	v_mfma_f32_16x16x32_bf16 v[62:65], v[146:149], v[186:189], v[62:65]
	v_mfma_f32_16x16x32_bf16 v[62:65], v[150:153], v[196:199], v[62:65]
	v_mfma_f32_16x16x32_bf16 v[54:57], v[146:149], v[200:203], v[54:57]
	v_mfma_f32_16x16x32_bf16 v[54:57], v[150:153], v[204:207], v[54:57]
	v_mfma_f32_16x16x32_bf16 v[46:49], v[146:149], v[208:211], v[46:49]
	v_mfma_f32_16x16x32_bf16 v[46:49], v[150:153], v[212:215], v[46:49]
	v_mfma_f32_16x16x32_bf16 v[66:69], v[154:157], v[178:181], v[66:69]
	v_mfma_f32_16x16x32_bf16 v[66:69], v[158:161], v[182:185], v[66:69]
	v_mfma_f32_16x16x32_bf16 v[58:61], v[154:157], v[186:189], v[58:61]
	v_mfma_f32_16x16x32_bf16 v[58:61], v[158:161], v[196:199], v[58:61]
	v_mfma_f32_16x16x32_bf16 v[50:53], v[154:157], v[200:203], v[50:53]
	v_mfma_f32_16x16x32_bf16 v[50:53], v[158:161], v[204:207], v[50:53]
	v_mfma_f32_16x16x32_bf16 v[42:45], v[154:157], v[208:211], v[42:45]
	v_mfma_f32_16x16x32_bf16 v[42:45], v[158:161], v[212:215], v[42:45]
	s_setprio 0
	s_barrier
; #define PG8_STAGE(bufoff, gbase, voff) do { const char* gb_ = (const char*)(gbase); asm volatile("" : "+s"(gb_)); _Pragma("unroll") for (int _i = 0; _i < 2; ++_i) { unsigned vo_ = (voff)[_i]; asm volatile("" : "+v"(vo_));        \
;         __builtin_amdgcn_global_load_lds((const unsigned*)(gb_ + vo_), (PG8_LAS unsigned*)(lds + (bufoff) + ldsw + _i * 8192), 16, 0, 0); } } while (0)
; #define PG8_LDA(dst, b, h) do { _Pragma("unroll") for (int m = 0; m < 4; ++m) _Pragma("unroll") for (int k = 0; k < 2; ++k) dst[m][k] = *(const PG8_LAS bf16x8*)(lds + PG8_SA(b, h) + aoff + m * 2048 + k * 1024); } while (0)
; #define PG8_WAIT_V(n) asm volatile("s_waitcnt vmcnt(" #n ")" ::: "memory")
; #define PG8_WAIT_L(n) asm volatile("s_waitcnt lgkmcnt(" #n ")" ::: "memory")
; #define PG8_BAR __builtin_amdgcn_s_barrier()
; #define PG8_SCHED __builtin_amdgcn_sched_barrier(0)
;     __device__ __forceinline__ void operator()(const f32x4 (&acc)[2][2][4][2], const Unit& u, int wr, int wc, int fr, int fq) const {
;         const int row0 = u.pm * BM + wr * 64 + fr, col0 = u.pn * BM + wc * 32 + 8 * fq, b = (u.pm * BM) / rows_per_batch;
;         const float* g = gate + (size_t)b * gate_bstride + col0;
;         float ssq[2][4];
; #pragma unroll
;         for (int ai = 0; ai < 2; ++ai)
; #pragma unroll
;             for (int m = 0; m < 4; ++m) ssq[ai][m] = 0.f;
;         f32x4 gv[2][2], Gv[2][2];
; #pragma unroll
;         for (int bj = 0; bj < 2; ++bj) { gv[bj][0] = *(const f32x4*)(g + bj * HALF); gv[bj][1] = *(const f32x4*)(g + bj * HALF + 4); Gv[bj][0] = (f32x4){0.f, 0.f, 0.f, 0.f}; Gv[bj][1] = (f32x4){0.f, 0.f, 0.f, 0.f};
;             if (Hn) { const float* sc = scnext + (size_t)b * gate_bstride + col0 + bj * HALF;
;                 Gv[bj][0] = *(const f32x4*)(gnext + col0 + bj * HALF) * (1.0f + *(const f32x4*)(sc)); Gv[bj][1] = *(const f32x4*)(gnext + col0 + bj * HALF + 4) * (1.0f + *(const f32x4*)(sc + 4)); } }
; template <class Epi, class Sched, bool ALIGN_EPI = false, bool SP2 = false>
; __device__ __forceinline__ void gemm_phase(PG8_LAS unsigned char* lds, const Gemm g, const Sched& S, const Epi& E) {
;     ...
;             PG8_LDA(At, 1, 1); PG8_STAGE(PG8_SB(1, 0), b3, voffB); PG8_STAGE(PG8_SB(1, 1), b3 + hstep, voffB); PG8_STAGE(PG8_SA(1, 0), a3, voffA);
;             PG8_WAIT_V(8); PG8_WAIT_L(0); PG8_BAR; PG8_MMA(1, 0, At, B0); PG8_MMA(1, 1, At, B1); PG8_BAR; PG8_SCHED;
	s_add_u32 s4, s8, 0x80
	s_addc_u32 s5, s9, 0
	v_mov_b32_e32 v195, v162
	s_add_i32 s10, s38, s15
	ds_read_b128 v[178:181], v194 offset:49152
	ds_read_b128 v[182:185], v194 offset:50176
	ds_read_b128 v[186:189], v194 offset:51200
	ds_read_b128 v[196:199], v194 offset:52224
	ds_read_b128 v[200:203], v194 offset:53248
	ds_read_b128 v[204:207], v194 offset:54272
	ds_read_b128 v[208:211], v194 offset:55296
	ds_read_b128 v[212:215], v194 offset:56320
	s_mov_b32 m0, s10
	s_nop 0
	global_load_lds_dwordx4 v195, s[4:5]
	v_mov_b32_e32 v195, v190
	s_add_i32 m0, s10, 0x2000
	s_nop 0
	global_load_lds_dwordx4 v195, s[4:5]
	s_add_u32 s4, s8, 0x160080
	s_addc_u32 s5, s9, 0
	v_mov_b32_e32 v195, v162
	s_add_i32 s8, s39, s15
	s_mov_b32 m0, s8
	s_nop 0
	global_load_lds_dwordx4 v195, s[4:5]
	v_mov_b32_e32 v195, v190
	s_add_i32 m0, s8, 0x2000
	s_nop 0
	global_load_lds_dwordx4 v195, s[4:5]
	v_mov_b32_e32 v195, v1
	s_mov_b32 m0, s24
	s_nop 0
	global_load_lds_dwordx4 v195, s[6:7]
	v_mov_b32_e32 v195, v164
	s_mov_b32 m0, s25
	s_nop 0
	global_load_lds_dwordx4 v195, s[6:7]
	s_waitcnt vmcnt(8)
	s_waitcnt lgkmcnt(0)
	s_barrier
	s_setprio 1
	s_waitcnt lgkmcnt(0)
	v_mfma_f32_16x16x32_bf16 v[110:113], v[74:77], v[178:181], v[110:113]
	v_mfma_f32_16x16x32_bf16 v[110:113], v[78:81], v[182:185], v[110:113]
	v_mfma_f32_16x16x32_bf16 v[94:97], v[74:77], v[186:189], v[94:97]
	v_mfma_f32_16x16x32_bf16 v[94:97], v[78:81], v[196:199], v[94:97]
	v_mfma_f32_16x16x32_bf16 v[86:89], v[74:77], v[200:203], v[86:89]
	v_mfma_f32_16x16x32_bf16 v[86:89], v[78:81], v[204:207], v[86:89]
	v_mfma_f32_16x16x32_bf16 v[34:37], v[74:77], v[208:211], v[34:37]
	v_mfma_f32_16x16x32_bf16 v[78:81], v[78:81], v[212:215], v[34:37]
	v_mfma_f32_16x16x32_bf16 v[106:109], v[98:101], v[178:181], v[106:109]
	v_mfma_f32_16x16x32_bf16 v[106:109], v[102:105], v[182:185], v[106:109]
	v_mfma_f32_16x16x32_bf16 v[90:93], v[98:101], v[186:189], v[90:93]
	v_mfma_f32_16x16x32_bf16 v[90:93], v[102:105], v[196:199], v[90:93]
	v_mfma_f32_16x16x32_bf16 v[82:85], v[98:101], v[200:203], v[82:85]
	v_mfma_f32_16x16x32_bf16 v[82:85], v[102:105], v[204:207], v[82:85]
	v_mfma_f32_16x16x32_bf16 v[34:37], v[98:101], v[208:211], v[38:41]
	v_mfma_f32_16x16x32_bf16 v[74:77], v[102:105], v[212:215], v[34:37]
	s_setprio 0
	s_setprio 1
	v_mfma_f32_16x16x32_bf16 v[30:33], v[146:149], v[178:181], v[30:33]
	v_mfma_f32_16x16x32_bf16 v[30:33], v[150:153], v[182:185], v[30:33]
	v_mfma_f32_16x16x32_bf16 v[22:25], v[146:149], v[186:189], v[22:25]
	v_mfma_f32_16x16x32_bf16 v[22:25], v[150:153], v[196:199], v[22:25]
	v_mfma_f32_16x16x32_bf16 v[14:17], v[146:149], v[200:203], v[14:17]
	v_mfma_f32_16x16x32_bf16 v[14:17], v[150:153], v[204:207], v[14:17]
	v_mfma_f32_16x16x32_bf16 v[6:9], v[146:149], v[208:211], v[6:9]
	v_mfma_f32_16x16x32_bf16 v[6:9], v[150:153], v[212:215], v[6:9]
	v_mfma_f32_16x16x32_bf16 v[26:29], v[154:157], v[178:181], v[26:29]
	v_mfma_f32_16x16x32_bf16 v[26:29], v[158:161], v[182:185], v[26:29]
	v_mfma_f32_16x16x32_bf16 v[18:21], v[154:157], v[186:189], v[18:21]
	v_mfma_f32_16x16x32_bf16 v[18:21], v[158:161], v[196:199], v[18:21]
	v_mfma_f32_16x16x32_bf16 v[10:13], v[154:157], v[200:203], v[10:13]
	v_mfma_f32_16x16x32_bf16 v[10:13], v[158:161], v[204:207], v[10:13]
	v_mfma_f32_16x16x32_bf16 v[2:5], v[154:157], v[208:211], v[2:5]
	v_mfma_f32_16x16x32_bf16 v[2:5], v[158:161], v[212:215], v[2:5]
	s_setprio 0
	s_barrier
	s_add_i32 s35, s35, 2
	s_add_u32 s31, s31, 0x100
	s_addc_u32 s34, s34, 0
	s_cmpk_gt_u32 s35, 0x55
	s_mov_b64 s[4:5], s[2:3]
	s_cbranch_scc0 .LBB0_707
	s_ashr_i32 s2, s29, 31
	s_lshr_b32 s2, s2, 27
	s_add_i32 s2, s29, s2
	s_ashr_i32 s2, s2, 5
	v_lshl_or_b32 v156, s30, 8, v193
	s_mul_i32 s5, s2, 0xc000
	v_ashrrev_i32_e32 v157, 31, v156
	s_mul_hi_i32 s4, s2, 0xc000
	s_add_u32 s2, s20, s5
	s_addc_u32 s3, s21, s4
	v_lshlrev_b64 v[34:35], 2, v[156:157]
	v_lshl_add_u64 v[38:39], s[2:3], 0, v[34:35]
	global_load_dwordx4 v[98:101], v[38:39], off offset:16
	global_load_dwordx4 v[102:105], v[38:39], off
	s_add_u32 s2, s22, s5
	s_addc_u32 s3, s23, s4
	v_lshl_add_u64 v[148:149], s[2:3], 0, v[34:35]
	v_lshl_add_u64 v[146:147], s[48:49], 0, v[34:35]
	v_mov_b32_e32 v158, 0
	v_cndmask_b32_e64 v34, 0, 1, s[46:47]
	v_cmp_ne_u32_e64 s[2:3], 1, v34
	s_andn2_b64 vcc, exec, s[46:47]
	v_mov_b32_e32 v159, v158
	v_mov_b32_e32 v160, v158
	v_mov_b32_e32 v161, v158
	v_mov_b32_e32 v178, v158
	v_mov_b32_e32 v179, v158
	v_mov_b32_e32 v180, v158
	v_mov_b32_e32 v181, v158
	s_cbranch_vccnz .LBB0_710
	global_load_dwordx4 v[34:37], v[148:149], off
	global_load_dwordx4 v[150:153], v[148:149], off offset:16
	global_load_dwordx4 v[158:161], v[146:147], off
	global_load_dwordx4 v[178:181], v[146:147], off offset:16
	s_waitcnt vmcnt(0)
	v_pk_add_f32 v[36:37], v[36:37], 1.0 op_sel_hi:[1,0]
	v_pk_add_f32 v[34:35], v[34:35], 1.0 op_sel_hi:[1,0]
	v_pk_add_f32 v[40:41], v[152:153], 1.0 op_sel_hi:[1,0]
	v_pk_add_f32 v[150:151], v[150:151], 1.0 op_sel_hi:[1,0]
	v_pk_mul_f32 v[160:161], v[160:161], v[36:37]
	v_pk_mul_f32 v[158:159], v[158:159], v[34:35]
	v_pk_mul_f32 v[180:181], v[180:181], v[40:41]
	v_pk_mul_f32 v[178:179], v[178:179], v[150:151]
